# baseline (speedup 1.0000x reference)
; #define PG8_STAGE(bufoff, gbase, voff) do { _Pragma("unroll") for (int _i = 0; _i < 2; ++_i) \
;         __builtin_amdgcn_global_load_lds((const unsigned*)((const char*)(gbase) + (voff)[_i]), (PG8_LAS unsigned*)(lds + (bufoff) + ldsw + _i * 8192), 16, 0, 0); } while (0)
; #define PG8_LDA(dst, b, h) do { _Pragma("unroll") for (int m = 0; m < 4; ++m) _Pragma("unroll") for (int k = 0; k < 2; ++k) dst[m][k] = *(const PG8_LAS bf16x8*)(lds + PG8_SA(b, h) + aoff + m * 2048 + k * 1024); } while (0)
; #define PG8_LDB(dst, b, h) do { _Pragma("unroll") for (int n = 0; n < 2; ++n) _Pragma("unroll") for (int k = 0; k < 2; ++k) dst[n][k] = *(const PG8_LAS bf16x8*)(lds + PG8_SB(b, h) + boff + n * 2048 + k * 1024); } while (0)
; #define PG8_MMA(ai, bj, At, Bt) do { __builtin_amdgcn_s_setprio(1); _Pragma("unroll") for (int m = 0; m < 4; ++m) _Pragma("unroll") for (int n = 0; n < 2; ++n) _Pragma("unroll") for (int k = 0; k < 2; ++k) \
;         acc[ai][bj][m][n] = __builtin_amdgcn_mfma_f32_16x16x32_bf16(Bt[n][k], At[m][k], acc[ai][bj][m][n], 0, 0, 0); __builtin_amdgcn_s_setprio(0); } while (0)
; #define PG8_WAIT_V(n) asm volatile("s_waitcnt vmcnt(" #n ")" ::: "memory")
; #define PG8_WAIT_L(n) asm volatile("s_waitcnt lgkmcnt(" #n ")" ::: "memory")
; #define PG8_BAR __builtin_amdgcn_s_barrier()
; #define PG8_SCHED __builtin_amdgcn_sched_barrier(0)
; template <class Epi, class Sched, bool ALIGN_EPI = false, bool SP2 = false>
; __device__ __forceinline__ void gemm_phase(PG8_LAS unsigned char* lds, const Gemm g, const Sched& S, const Epi& E) {
;     ...
;             PG8_LDB(B0, 0, 0); PG8_LDB(B1, 0, 1); PG8_SCHED; PG8_LDA(At, 0, 0); PG8_STAGE(PG8_SA(1, 1), a1 + hstepA, voffA);
;             PG8_WAIT_V(8); PG8_WAIT_L(0); PG8_BAR; PG8_MMA(0, 0, At, B0); PG8_MMA(0, 1, At, B1); PG8_BAR; PG8_SCHED;
;             PG8_LDA(At, 0, 1); PG8_STAGE(PG8_SB(0, 0), b2, voffB); PG8_STAGE(PG8_SB(0, 1), b2 + hstep, voffB); PG8_STAGE(PG8_SA(0, 0), a2, voffA);
;             PG8_WAIT_V(8); PG8_WAIT_L(0); PG8_BAR; PG8_MMA(1, 0, At, B0); PG8_MMA(1, 1, At, B1); PG8_BAR; PG8_SCHED;
;             PG8_LDB(B0, 1, 0); PG8_LDB(B1, 1, 1); PG8_SCHED; PG8_LDA(At, 1, 0); PG8_STAGE(PG8_SA(0, 1), a2 + hstepA, voffA);
;             PG8_WAIT_V(8); PG8_WAIT_L(0); PG8_BAR; PG8_MMA(0, 0, At, B0); PG8_MMA(0, 1, At, B1); PG8_BAR; PG8_SCHED;
.Lpf_skip:
	s_add_u32 s12, s10, 0xfffc0080
	s_addc_u32 s13, s11, -1
	s_add_i32 s94, 0, 0x10000
	s_cmp_eq_u32 vcc_lo, 12
	s_cselect_b32 s45, s21, s13
	s_cselect_b32 s44, s28, s12
	v_add_u32_e32 v0, s94, v179
	s_cselect_b32 s13, s43, s63
	s_cselect_b32 s12, s46, s47
	s_add_i32 vcc_hi, 0, 0x14000
	ds_read_b128 v[130:133], v0
	ds_read_b128 v[134:137], v0 offset:1024
	ds_read_b128 v[138:141], v0 offset:2048
	ds_read_b128 v[142:145], v0 offset:3072
	v_add_u32_e32 v0, vcc_hi, v179
	ds_read_b128 v[146:149], v0
	ds_read_b128 v[170:173], v0 offset:1024
	ds_read_b128 v[190:193], v0 offset:2048
	ds_read_b128 v[194:197], v0 offset:3072
	v_lshl_add_u64 v[150:151], s[10:11], 0, v[162:163]
	s_add_i32 m0, s17, 0xc000
	ds_read_b128 v[198:201], v186
	ds_read_b128 v[202:205], v186 offset:1024
	ds_read_b128 v[206:209], v186 offset:2048
	ds_read_b128 v[210:213], v186 offset:3072
	ds_read_b128 v[214:217], v186 offset:4096
	ds_read_b128 v[218:221], v186 offset:5120
	ds_read_b128 v[222:225], v186 offset:6144
	ds_read_b128 v[226:229], v186 offset:7168
	global_load_lds_dwordx4 v[150:151], off
	v_lshl_add_u64 v[150:151], s[10:11], 0, v[164:165]
	s_add_i32 m0, s17, 0xe000
	s_nop 0
	global_load_lds_dwordx4 v[150:151], off
	s_waitcnt vmcnt(8)
	s_waitcnt lgkmcnt(0)
	s_barrier
	s_setprio 1
	s_waitcnt lgkmcnt(0)
	v_mfma_f32_16x16x32_bf16 v[126:129], v[130:133], v[198:201], 0
	v_mfma_f32_16x16x32_bf16 v[122:125], v[138:141], v[198:201], 0
	v_mfma_f32_16x16x32_bf16 v[110:113], v[130:133], v[206:209], 0
	v_mfma_f32_16x16x32_bf16 v[106:109], v[138:141], v[206:209], 0
	v_mfma_f32_16x16x32_bf16 v[94:97], v[130:133], v[214:217], 0
	v_mfma_f32_16x16x32_bf16 v[90:93], v[138:141], v[214:217], 0
	v_mfma_f32_16x16x32_bf16 v[78:81], v[130:133], v[222:225], 0
	v_mfma_f32_16x16x32_bf16 v[74:77], v[138:141], v[222:225], 0
	v_mfma_f32_16x16x32_bf16 v[126:129], v[134:137], v[202:205], v[126:129]
	v_mfma_f32_16x16x32_bf16 v[122:125], v[142:145], v[202:205], v[122:125]
	v_mfma_f32_16x16x32_bf16 v[110:113], v[134:137], v[210:213], v[110:113]
	v_mfma_f32_16x16x32_bf16 v[106:109], v[142:145], v[210:213], v[106:109]
	v_mfma_f32_16x16x32_bf16 v[94:97], v[134:137], v[218:221], v[94:97]
	v_mfma_f32_16x16x32_bf16 v[90:93], v[142:145], v[218:221], v[90:93]
	v_mfma_f32_16x16x32_bf16 v[78:81], v[134:137], v[226:229], v[78:81]
	v_mfma_f32_16x16x32_bf16 v[74:77], v[142:145], v[226:229], v[74:77]
	v_mfma_f32_16x16x32_bf16 v[118:121], v[146:149], v[198:201], 0
	v_mfma_f32_16x16x32_bf16 v[114:117], v[190:193], v[198:201], 0
	v_mfma_f32_16x16x32_bf16 v[102:105], v[146:149], v[206:209], 0
	v_mfma_f32_16x16x32_bf16 v[98:101], v[190:193], v[206:209], 0
	v_mfma_f32_16x16x32_bf16 v[86:89], v[146:149], v[214:217], 0
	v_mfma_f32_16x16x32_bf16 v[82:85], v[190:193], v[214:217], 0
	v_mfma_f32_16x16x32_bf16 v[70:73], v[146:149], v[222:225], 0
	v_mfma_f32_16x16x32_bf16 v[66:69], v[190:193], v[222:225], 0
	v_mfma_f32_16x16x32_bf16 v[118:121], v[170:173], v[202:205], v[118:121]
	v_mfma_f32_16x16x32_bf16 v[114:117], v[194:197], v[202:205], v[114:117]
	v_mfma_f32_16x16x32_bf16 v[102:105], v[170:173], v[210:213], v[102:105]
	v_mfma_f32_16x16x32_bf16 v[98:101], v[194:197], v[210:213], v[98:101]
	v_mfma_f32_16x16x32_bf16 v[86:89], v[170:173], v[218:221], v[86:89]
	v_mfma_f32_16x16x32_bf16 v[82:85], v[194:197], v[218:221], v[82:85]
	v_mfma_f32_16x16x32_bf16 v[70:73], v[170:173], v[226:229], v[70:73]
	v_mfma_f32_16x16x32_bf16 v[66:69], v[194:197], v[226:229], v[66:69]
	s_setprio 0
	s_barrier
	s_add_i32 s94, s94, s16
	v_lshl_add_u64 v[150:151], s[12:13], 0, v[156:157]
	s_mov_b32 m0, s94
	ds_read_b128 v[198:201], v186 offset:16384
	ds_read_b128 v[202:205], v186 offset:17408
	ds_read_b128 v[206:209], v186 offset:18432
	ds_read_b128 v[210:213], v186 offset:19456
	ds_read_b128 v[214:217], v186 offset:20480
	ds_read_b128 v[218:221], v186 offset:21504
	ds_read_b128 v[222:225], v186 offset:22528
	ds_read_b128 v[226:229], v186 offset:23552
	global_load_lds_dwordx4 v[150:151], off
	s_add_i32 m0, s94, 0x2000
	s_add_u32 s94, s12, 0x40000
	v_lshl_add_u64 v[166:167], s[12:13], 0, v[160:161]
	s_addc_u32 s95, s13, 0
	s_add_i32 vcc_hi, vcc_hi, s16
	global_load_lds_dwordx4 v[166:167], off
	v_lshl_add_u64 v[230:231], s[94:95], 0, v[156:157]
	s_mov_b32 m0, vcc_hi
	v_lshl_add_u64 v[232:233], s[44:45], 0, v[158:159]
	global_load_lds_dwordx4 v[230:231], off
	v_lshl_add_u64 v[230:231], s[94:95], 0, v[160:161]
	s_add_i32 m0, vcc_hi, 0x2000
	s_nop 0
	global_load_lds_dwordx4 v[230:231], off
	v_lshl_add_u64 v[230:231], s[44:45], 0, v[154:155]
	s_mov_b32 m0, s17
	s_nop 0
	global_load_lds_dwordx4 v[230:231], off
	s_mov_b32 m0, s51
	s_nop 0
	global_load_lds_dwordx4 v[232:233], off
	s_waitcnt vmcnt(8)
	s_waitcnt lgkmcnt(0)
	s_barrier
; #define PG8_STAGE(bufoff, gbase, voff) do { _Pragma("unroll") for (int _i = 0; _i < 2; ++_i) \
;         __builtin_amdgcn_global_load_lds((const unsigned*)((const char*)(gbase) + (voff)[_i]), (PG8_LAS unsigned*)(lds + (bufoff) + ldsw + _i * 8192), 16, 0, 0); } while (0)
; #define PG8_LDA(dst, b, h) do { _Pragma("unroll") for (int m = 0; m < 4; ++m) _Pragma("unroll") for (int k = 0; k < 2; ++k) dst[m][k] = *(const PG8_LAS bf16x8*)(lds + PG8_SA(b, h) + aoff + m * 2048 + k * 1024); } while (0)
; #define PG8_MMA(ai, bj, At, Bt) do { __builtin_amdgcn_s_setprio(1); _Pragma("unroll") for (int m = 0; m < 4; ++m) _Pragma("unroll") for (int n = 0; n < 2; ++n) _Pragma("unroll") for (int k = 0; k < 2; ++k) \
;         acc[ai][bj][m][n] = __builtin_amdgcn_mfma_f32_16x16x32_bf16(Bt[n][k], At[m][k], acc[ai][bj][m][n], 0, 0, 0); __builtin_amdgcn_s_setprio(0); } while (0)
; #define PG8_WAIT_V(n) asm volatile("s_waitcnt vmcnt(" #n ")" ::: "memory")
; #define PG8_WAIT_L(n) asm volatile("s_waitcnt lgkmcnt(" #n ")" ::: "memory")
; #define PG8_BAR __builtin_amdgcn_s_barrier()
; #define PG8_SCHED __builtin_amdgcn_sched_barrier(0)
; template <class Epi, class Sched, bool ALIGN_EPI = false, bool SP2 = false>
; __device__ __forceinline__ void gemm_phase(PG8_LAS unsigned char* lds, const Gemm g, const Sched& S, const Epi& E) {
;     ...
;             PG8_WAIT_V(8); PG8_WAIT_L(0); PG8_BAR; PG8_MMA(0, 0, At, B0); PG8_MMA(0, 1, At, B1); PG8_BAR; PG8_SCHED;
;             PG8_LDA(At, 1, 1); PG8_STAGE(PG8_SB(1, 0), b3, voffB); PG8_STAGE(PG8_SB(1, 1), b3 + hstep, voffB); PG8_STAGE(PG8_SA(1, 0), a3, voffA);
;             PG8_WAIT_V(8); PG8_WAIT_L(0); PG8_BAR; PG8_MMA(1, 0, At, B0); PG8_MMA(1, 1, At, B1); PG8_BAR; PG8_SCHED;
	s_setprio 1
	s_waitcnt lgkmcnt(0)
	v_mfma_f32_16x16x32_bf16 v[62:65], v[130:133], v[198:201], 0
	v_mfma_f32_16x16x32_bf16 v[58:61], v[138:141], v[198:201], 0
	v_mfma_f32_16x16x32_bf16 v[46:49], v[130:133], v[206:209], 0
	v_mfma_f32_16x16x32_bf16 v[42:45], v[138:141], v[206:209], 0
	v_mfma_f32_16x16x32_bf16 v[30:33], v[130:133], v[214:217], 0
	v_mfma_f32_16x16x32_bf16 v[26:29], v[138:141], v[214:217], 0
	v_mfma_f32_16x16x32_bf16 v[14:17], v[130:133], v[222:225], 0
	v_mfma_f32_16x16x32_bf16 v[10:13], v[138:141], v[222:225], 0
	v_mfma_f32_16x16x32_bf16 v[62:65], v[134:137], v[202:205], v[62:65]
	v_mfma_f32_16x16x32_bf16 v[58:61], v[142:145], v[202:205], v[58:61]
	v_mfma_f32_16x16x32_bf16 v[46:49], v[134:137], v[210:213], v[46:49]
	v_mfma_f32_16x16x32_bf16 v[42:45], v[142:145], v[210:213], v[42:45]
	v_mfma_f32_16x16x32_bf16 v[30:33], v[134:137], v[218:221], v[30:33]
	v_mfma_f32_16x16x32_bf16 v[26:29], v[142:145], v[218:221], v[26:29]
	v_mfma_f32_16x16x32_bf16 v[14:17], v[134:137], v[226:229], v[14:17]
	v_mfma_f32_16x16x32_bf16 v[10:13], v[142:145], v[226:229], v[10:13]
	v_mfma_f32_16x16x32_bf16 v[54:57], v[146:149], v[198:201], 0
	v_mfma_f32_16x16x32_bf16 v[50:53], v[190:193], v[198:201], 0
	v_mfma_f32_16x16x32_bf16 v[38:41], v[146:149], v[206:209], 0
	v_mfma_f32_16x16x32_bf16 v[34:37], v[190:193], v[206:209], 0
	v_mfma_f32_16x16x32_bf16 v[22:25], v[146:149], v[214:217], 0
	v_mfma_f32_16x16x32_bf16 v[18:21], v[190:193], v[214:217], 0
	v_mfma_f32_16x16x32_bf16 v[6:9], v[146:149], v[222:225], 0
	v_mfma_f32_16x16x32_bf16 v[2:5], v[190:193], v[222:225], 0
	v_mfma_f32_16x16x32_bf16 v[54:57], v[170:173], v[202:205], v[54:57]
	v_mfma_f32_16x16x32_bf16 v[50:53], v[194:197], v[202:205], v[50:53]
	v_mfma_f32_16x16x32_bf16 v[38:41], v[170:173], v[210:213], v[38:41]
	v_mfma_f32_16x16x32_bf16 v[34:37], v[194:197], v[210:213], v[34:37]
	v_mfma_f32_16x16x32_bf16 v[22:25], v[170:173], v[218:221], v[22:25]
	v_mfma_f32_16x16x32_bf16 v[18:21], v[194:197], v[218:221], v[18:21]
	v_mfma_f32_16x16x32_bf16 v[6:9], v[170:173], v[226:229], v[6:9]
	v_mfma_f32_16x16x32_bf16 v[2:5], v[194:197], v[226:229], v[2:5]
	s_setprio 0
	s_barrier
	s_add_i32 s94, 0, 0x18000
	v_add_u32_e32 v0, s94, v179
	s_add_i32 s95, 0, 0x1c000
	ds_read_b128 v[130:133], v0
	ds_read_b128 v[134:137], v0 offset:1024
	ds_read_b128 v[138:141], v0 offset:2048
	ds_read_b128 v[142:145], v0 offset:3072
	v_add_u32_e32 v0, s95, v179
	ds_read_b128 v[146:149], v0
	ds_read_b128 v[170:173], v0 offset:1024
	ds_read_b128 v[190:193], v0 offset:2048
	ds_read_b128 v[194:197], v0 offset:3072
	s_add_u32 s44, s44, 0x40000
	s_addc_u32 s45, s45, 0
	s_mov_b32 m0, s35
	v_lshl_add_u64 v[234:235], s[44:45], 0, v[154:155]
	ds_read_b128 v[198:201], v186 offset:32768
	ds_read_b128 v[202:205], v186 offset:33792
	ds_read_b128 v[206:209], v186 offset:34816
	ds_read_b128 v[210:213], v186 offset:35840
	ds_read_b128 v[214:217], v186 offset:36864
	ds_read_b128 v[218:221], v186 offset:37888
	ds_read_b128 v[222:225], v186 offset:38912
	ds_read_b128 v[226:229], v186 offset:39936
	global_load_lds_dwordx4 v[234:235], off
	v_lshl_add_u64 v[234:235], s[44:45], 0, v[158:159]
	s_mov_b32 m0, s30
	s_nop 0
	global_load_lds_dwordx4 v[234:235], off
	s_waitcnt vmcnt(8)
	s_waitcnt lgkmcnt(0)
	s_barrier
	s_setprio 1
	s_waitcnt lgkmcnt(0)
	v_mfma_f32_16x16x32_bf16 v[126:129], v[130:133], v[198:201], v[126:129]
	v_mfma_f32_16x16x32_bf16 v[122:125], v[138:141], v[198:201], v[122:125]
	v_mfma_f32_16x16x32_bf16 v[110:113], v[130:133], v[206:209], v[110:113]
	v_mfma_f32_16x16x32_bf16 v[106:109], v[138:141], v[206:209], v[106:109]
	v_mfma_f32_16x16x32_bf16 v[94:97], v[130:133], v[214:217], v[94:97]
	v_mfma_f32_16x16x32_bf16 v[90:93], v[138:141], v[214:217], v[90:93]
	v_mfma_f32_16x16x32_bf16 v[78:81], v[130:133], v[222:225], v[78:81]
	v_mfma_f32_16x16x32_bf16 v[74:77], v[138:141], v[222:225], v[74:77]
	v_mfma_f32_16x16x32_bf16 v[126:129], v[134:137], v[202:205], v[126:129]
	v_mfma_f32_16x16x32_bf16 v[122:125], v[142:145], v[202:205], v[122:125]
	v_mfma_f32_16x16x32_bf16 v[110:113], v[134:137], v[210:213], v[110:113]
	v_mfma_f32_16x16x32_bf16 v[106:109], v[142:145], v[210:213], v[106:109]
	v_mfma_f32_16x16x32_bf16 v[94:97], v[134:137], v[218:221], v[94:97]
	v_mfma_f32_16x16x32_bf16 v[90:93], v[142:145], v[218:221], v[90:93]
	v_mfma_f32_16x16x32_bf16 v[78:81], v[134:137], v[226:229], v[78:81]
	v_mfma_f32_16x16x32_bf16 v[74:77], v[142:145], v[226:229], v[74:77]
	v_mfma_f32_16x16x32_bf16 v[118:121], v[146:149], v[198:201], v[118:121]
	v_mfma_f32_16x16x32_bf16 v[114:117], v[190:193], v[198:201], v[114:117]
	v_mfma_f32_16x16x32_bf16 v[102:105], v[146:149], v[206:209], v[102:105]
	v_mfma_f32_16x16x32_bf16 v[98:101], v[190:193], v[206:209], v[98:101]
	v_mfma_f32_16x16x32_bf16 v[86:89], v[146:149], v[214:217], v[86:89]
	v_mfma_f32_16x16x32_bf16 v[82:85], v[190:193], v[214:217], v[82:85]
	v_mfma_f32_16x16x32_bf16 v[70:73], v[146:149], v[222:225], v[70:73]
	v_mfma_f32_16x16x32_bf16 v[66:69], v[190:193], v[222:225], v[66:69]
	v_mfma_f32_16x16x32_bf16 v[118:121], v[170:173], v[202:205], v[118:121]
	v_mfma_f32_16x16x32_bf16 v[114:117], v[194:197], v[202:205], v[114:117]
	v_mfma_f32_16x16x32_bf16 v[102:105], v[170:173], v[210:213], v[102:105]
	v_mfma_f32_16x16x32_bf16 v[98:101], v[194:197], v[210:213], v[98:101]
	v_mfma_f32_16x16x32_bf16 v[86:89], v[170:173], v[218:221], v[86:89]
	v_mfma_f32_16x16x32_bf16 v[82:85], v[194:197], v[218:221], v[82:85]
	v_mfma_f32_16x16x32_bf16 v[70:73], v[170:173], v[226:229], v[70:73]
	v_mfma_f32_16x16x32_bf16 v[66:69], v[194:197], v[226:229], v[66:69]
	s_setprio 0
	s_barrier
; #define PG8_STAGE(bufoff, gbase, voff) do { _Pragma("unroll") for (int _i = 0; _i < 2; ++_i) \
;         __builtin_amdgcn_global_load_lds((const unsigned*)((const char*)(gbase) + (voff)[_i]), (PG8_LAS unsigned*)(lds + (bufoff) + ldsw + _i * 8192), 16, 0, 0); } while (0)
; #define PG8_LDA(dst, b, h) do { _Pragma("unroll") for (int m = 0; m < 4; ++m) _Pragma("unroll") for (int k = 0; k < 2; ++k) dst[m][k] = *(const PG8_LAS bf16x8*)(lds + PG8_SA(b, h) + aoff + m * 2048 + k * 1024); } while (0)
; #define PG8_LDB(dst, b, h) do { _Pragma("unroll") for (int n = 0; n < 2; ++n) _Pragma("unroll") for (int k = 0; k < 2; ++k) dst[n][k] = *(const PG8_LAS bf16x8*)(lds + PG8_SB(b, h) + boff + n * 2048 + k * 1024); } while (0)
; #define PG8_MMA(ai, bj, At, Bt) do { __builtin_amdgcn_s_setprio(1); _Pragma("unroll") for (int m = 0; m < 4; ++m) _Pragma("unroll") for (int n = 0; n < 2; ++n) _Pragma("unroll") for (int k = 0; k < 2; ++k) \
;         acc[ai][bj][m][n] = __builtin_amdgcn_mfma_f32_16x16x32_bf16(Bt[n][k], At[m][k], acc[ai][bj][m][n], 0, 0, 0); __builtin_amdgcn_s_setprio(0); } while (0)
; #define PG8_WAIT_V(n) asm volatile("s_waitcnt vmcnt(" #n ")" ::: "memory")
; #define PG8_WAIT_L(n) asm volatile("s_waitcnt lgkmcnt(" #n ")" ::: "memory")
; #define PG8_BAR __builtin_amdgcn_s_barrier()
; #define PG8_SCHED __builtin_amdgcn_sched_barrier(0)
; template <class Epi, class Sched, bool ALIGN_EPI = false, bool SP2 = false>
; __device__ __forceinline__ void gemm_phase(PG8_LAS unsigned char* lds, const Gemm g, const Sched& S, const Epi& E) {
;     ...
;             PG8_WAIT_V(8); PG8_WAIT_L(0); PG8_BAR; PG8_MMA(0, 0, At, B0); PG8_MMA(0, 1, At, B1); PG8_BAR; PG8_SCHED;
;             PG8_LDA(At, 1, 1); PG8_STAGE(PG8_SB(1, 0), b3, voffB); PG8_STAGE(PG8_SB(1, 1), b3 + hstep, voffB); PG8_STAGE(PG8_SA(1, 0), a3, voffA);
;             PG8_WAIT_V(8); PG8_WAIT_L(0); PG8_BAR; PG8_MMA(1, 0, At, B0); PG8_MMA(1, 1, At, B1); PG8_BAR; PG8_SCHED;
;             } else {
;             PG8_LDB(B0, 0, 0); PG8_SCHED; PG8_LDA(At, 0, 0); PG8_STAGE(PG8_SA(1, 1), a1 + hstepA, voffA);
	s_add_i32 s44, s94, s16
	v_lshl_add_u64 v[150:151], v[150:151], 0, s[48:49]
	s_mov_b32 m0, s44
	ds_read_b128 v[198:201], v186 offset:49152
	ds_read_b128 v[202:205], v186 offset:50176
	ds_read_b128 v[206:209], v186 offset:51200
	ds_read_b128 v[210:213], v186 offset:52224
	ds_read_b128 v[214:217], v186 offset:53248
	ds_read_b128 v[218:221], v186 offset:54272
	ds_read_b128 v[222:225], v186 offset:55296
	ds_read_b128 v[226:229], v186 offset:56320
	global_load_lds_dwordx4 v[150:151], off
	s_add_i32 m0, s44, 0x2000
	s_add_u32 s12, s12, 0x40080
	v_lshl_add_u64 v[150:151], v[166:167], 0, s[48:49]
	s_addc_u32 s13, s13, 0
	s_add_i32 s44, s95, s16
	global_load_lds_dwordx4 v[150:151], off
	v_lshl_add_u64 v[150:151], s[12:13], 0, v[156:157]
	s_mov_b32 m0, s44
	s_nop 0
	global_load_lds_dwordx4 v[150:151], off
	v_lshl_add_u64 v[150:151], s[12:13], 0, v[160:161]
	s_add_i32 m0, s44, 0x2000
	s_nop 0
	global_load_lds_dwordx4 v[150:151], off
	v_lshl_add_u64 v[150:151], v[230:231], 0, s[48:49]
	s_mov_b32 m0, s59
	s_nop 0
	global_load_lds_dwordx4 v[150:151], off
	v_lshl_add_u64 v[150:151], v[232:233], 0, s[48:49]
	s_mov_b32 m0, s86
	s_nop 0
	global_load_lds_dwordx4 v[150:151], off
	s_waitcnt vmcnt(8)
	s_waitcnt lgkmcnt(0)
	s_barrier
	s_setprio 1
	s_waitcnt lgkmcnt(0)
	v_mfma_f32_16x16x32_bf16 v[62:65], v[130:133], v[198:201], v[62:65]
	v_mfma_f32_16x16x32_bf16 v[58:61], v[138:141], v[198:201], v[58:61]
	v_mfma_f32_16x16x32_bf16 v[46:49], v[130:133], v[206:209], v[46:49]
	v_mfma_f32_16x16x32_bf16 v[42:45], v[138:141], v[206:209], v[42:45]
	v_mfma_f32_16x16x32_bf16 v[30:33], v[130:133], v[214:217], v[30:33]
	v_mfma_f32_16x16x32_bf16 v[26:29], v[138:141], v[214:217], v[26:29]
	v_mfma_f32_16x16x32_bf16 v[14:17], v[130:133], v[222:225], v[14:17]
	v_mfma_f32_16x16x32_bf16 v[10:13], v[138:141], v[222:225], v[10:13]
	v_mfma_f32_16x16x32_bf16 v[62:65], v[134:137], v[202:205], v[62:65]
	v_mfma_f32_16x16x32_bf16 v[58:61], v[142:145], v[202:205], v[58:61]
	v_mfma_f32_16x16x32_bf16 v[46:49], v[134:137], v[210:213], v[46:49]
	v_mfma_f32_16x16x32_bf16 v[42:45], v[142:145], v[210:213], v[42:45]
	v_mfma_f32_16x16x32_bf16 v[30:33], v[134:137], v[218:221], v[30:33]
	v_mfma_f32_16x16x32_bf16 v[26:29], v[142:145], v[218:221], v[26:29]
	v_mfma_f32_16x16x32_bf16 v[14:17], v[134:137], v[226:229], v[14:17]
	v_mfma_f32_16x16x32_bf16 v[10:13], v[142:145], v[226:229], v[10:13]
	v_mfma_f32_16x16x32_bf16 v[54:57], v[146:149], v[198:201], v[54:57]
	v_mfma_f32_16x16x32_bf16 v[50:53], v[190:193], v[198:201], v[50:53]
	v_mfma_f32_16x16x32_bf16 v[38:41], v[146:149], v[206:209], v[38:41]
	v_mfma_f32_16x16x32_bf16 v[34:37], v[190:193], v[206:209], v[34:37]
	v_mfma_f32_16x16x32_bf16 v[22:25], v[146:149], v[214:217], v[22:25]
	v_mfma_f32_16x16x32_bf16 v[18:21], v[190:193], v[214:217], v[18:21]
	v_mfma_f32_16x16x32_bf16 v[6:9], v[146:149], v[222:225], v[6:9]
	v_mfma_f32_16x16x32_bf16 v[2:5], v[190:193], v[222:225], v[2:5]
	v_mfma_f32_16x16x32_bf16 v[54:57], v[170:173], v[202:205], v[54:57]
	v_mfma_f32_16x16x32_bf16 v[50:53], v[194:197], v[202:205], v[50:53]
	v_mfma_f32_16x16x32_bf16 v[38:41], v[170:173], v[210:213], v[38:41]
	v_mfma_f32_16x16x32_bf16 v[34:37], v[194:197], v[210:213], v[34:37]
	v_mfma_f32_16x16x32_bf16 v[22:25], v[170:173], v[218:221], v[22:25]
	v_mfma_f32_16x16x32_bf16 v[18:21], v[194:197], v[218:221], v[18:21]
	v_mfma_f32_16x16x32_bf16 v[6:9], v[170:173], v[226:229], v[6:9]
	v_mfma_f32_16x16x32_bf16 v[2:5], v[194:197], v[226:229], v[2:5]
	s_setprio 0
	s_barrier
	s_add_i32 vcc_lo, vcc_lo, 2
	s_add_u32 s10, s10, 0x100
	s_addc_u32 s11, s11, 0
	s_add_u32 s47, s47, 0x100
	s_addc_u32 s63, s63, 0
.LBB0_246:
	s_add_u32 s12, s10, 0xfffc0080
	s_addc_u32 s13, s11, -1
	s_add_i32 s94, 0, 0x10000
	s_cmp_eq_u32 vcc_lo, 12
	s_cselect_b32 s45, s21, s13
	s_cselect_b32 s44, s28, s12
	v_add_u32_e32 v0, s94, v179
	s_cselect_b32 s13, s43, s63
	s_cselect_b32 s12, s46, s47
	s_add_i32 vcc_hi, 0, 0x14000
	ds_read_b128 v[130:133], v0
	ds_read_b128 v[134:137], v0 offset:1024
	ds_read_b128 v[138:141], v0 offset:2048
	ds_read_b128 v[142:145], v0 offset:3072
	v_add_u32_e32 v0, vcc_hi, v179
	ds_read_b128 v[146:149], v0
	ds_read_b128 v[170:173], v0 offset:1024
	ds_read_b128 v[190:193], v0 offset:2048
	ds_read_b128 v[194:197], v0 offset:3072
	v_lshl_add_u64 v[150:151], s[10:11], 0, v[162:163]
	s_add_i32 m0, s17, 0xc000
	ds_read_b128 v[198:201], v186
	ds_read_b128 v[202:205], v186 offset:1024
	ds_read_b128 v[206:209], v186 offset:2048
	ds_read_b128 v[210:213], v186 offset:3072
	ds_read_b128 v[214:217], v186 offset:4096
	ds_read_b128 v[218:221], v186 offset:5120
	ds_read_b128 v[222:225], v186 offset:6144
	ds_read_b128 v[226:229], v186 offset:7168
	global_load_lds_dwordx4 v[150:151], off
	v_lshl_add_u64 v[150:151], s[10:11], 0, v[164:165]
	s_add_i32 m0, s17, 0xe000
	s_nop 0
	global_load_lds_dwordx4 v[150:151], off
	s_waitcnt vmcnt(8)
	s_waitcnt lgkmcnt(0)
	s_barrier
; #define PG8_STAGE(bufoff, gbase, voff) do { _Pragma("unroll") for (int _i = 0; _i < 2; ++_i) \
;         __builtin_amdgcn_global_load_lds((const unsigned*)((const char*)(gbase) + (voff)[_i]), (PG8_LAS unsigned*)(lds + (bufoff) + ldsw + _i * 8192), 16, 0, 0); } while (0)
; #define PG8_LDA(dst, b, h) do { _Pragma("unroll") for (int m = 0; m < 4; ++m) _Pragma("unroll") for (int k = 0; k < 2; ++k) dst[m][k] = *(const PG8_LAS bf16x8*)(lds + PG8_SA(b, h) + aoff + m * 2048 + k * 1024); } while (0)
; #define PG8_MMA(ai, bj, At, Bt) do { __builtin_amdgcn_s_setprio(1); _Pragma("unroll") for (int m = 0; m < 4; ++m) _Pragma("unroll") for (int n = 0; n < 2; ++n) _Pragma("unroll") for (int k = 0; k < 2; ++k) \
;         acc[ai][bj][m][n] = __builtin_amdgcn_mfma_f32_16x16x32_bf16(Bt[n][k], At[m][k], acc[ai][bj][m][n], 0, 0, 0); __builtin_amdgcn_s_setprio(0); } while (0)
; #define PG8_WAIT_V(n) asm volatile("s_waitcnt vmcnt(" #n ")" ::: "memory")
; #define PG8_WAIT_L(n) asm volatile("s_waitcnt lgkmcnt(" #n ")" ::: "memory")
; #define PG8_BAR __builtin_amdgcn_s_barrier()
; #define PG8_SCHED __builtin_amdgcn_sched_barrier(0)
; template <class Epi, class Sched, bool ALIGN_EPI = false, bool SP2 = false>
; __device__ __forceinline__ void gemm_phase(PG8_LAS unsigned char* lds, const Gemm g, const Sched& S, const Epi& E) {
;     ...
;             PG8_WAIT_V(8); PG8_WAIT_L(0); PG8_BAR; PG8_MMA(0, 0, At, B0); PG8_MMA(0, 1, At, B1); PG8_BAR; PG8_SCHED;
;             PG8_LDA(At, 0, 1); PG8_STAGE(PG8_SB(0, 0), b2, voffB); PG8_STAGE(PG8_SB(0, 1), b2 + hstep, voffB); PG8_STAGE(PG8_SA(0, 0), a2, voffA);
;             PG8_WAIT_V(8); PG8_WAIT_L(0); PG8_BAR; PG8_MMA(1, 0, At, B0); PG8_MMA(1, 1, At, B1); PG8_BAR; PG8_SCHED;
	s_setprio 1
	s_waitcnt lgkmcnt(0)
	v_mfma_f32_16x16x32_bf16 v[126:129], v[130:133], v[198:201], v[126:129]
	v_mfma_f32_16x16x32_bf16 v[122:125], v[138:141], v[198:201], v[122:125]
	v_mfma_f32_16x16x32_bf16 v[110:113], v[130:133], v[206:209], v[110:113]
	v_mfma_f32_16x16x32_bf16 v[106:109], v[138:141], v[206:209], v[106:109]
	v_mfma_f32_16x16x32_bf16 v[94:97], v[130:133], v[214:217], v[94:97]
	v_mfma_f32_16x16x32_bf16 v[90:93], v[138:141], v[214:217], v[90:93]
	v_mfma_f32_16x16x32_bf16 v[78:81], v[130:133], v[222:225], v[78:81]
	v_mfma_f32_16x16x32_bf16 v[74:77], v[138:141], v[222:225], v[74:77]
	v_mfma_f32_16x16x32_bf16 v[126:129], v[134:137], v[202:205], v[126:129]
	v_mfma_f32_16x16x32_bf16 v[122:125], v[142:145], v[202:205], v[122:125]
	v_mfma_f32_16x16x32_bf16 v[110:113], v[134:137], v[210:213], v[110:113]
	v_mfma_f32_16x16x32_bf16 v[106:109], v[142:145], v[210:213], v[106:109]
	v_mfma_f32_16x16x32_bf16 v[94:97], v[134:137], v[218:221], v[94:97]
	v_mfma_f32_16x16x32_bf16 v[90:93], v[142:145], v[218:221], v[90:93]
	v_mfma_f32_16x16x32_bf16 v[78:81], v[134:137], v[226:229], v[78:81]
	v_mfma_f32_16x16x32_bf16 v[74:77], v[142:145], v[226:229], v[74:77]
	v_mfma_f32_16x16x32_bf16 v[118:121], v[146:149], v[198:201], v[118:121]
	v_mfma_f32_16x16x32_bf16 v[114:117], v[190:193], v[198:201], v[114:117]
	v_mfma_f32_16x16x32_bf16 v[102:105], v[146:149], v[206:209], v[102:105]
	v_mfma_f32_16x16x32_bf16 v[98:101], v[190:193], v[206:209], v[98:101]
	v_mfma_f32_16x16x32_bf16 v[86:89], v[146:149], v[214:217], v[86:89]
	v_mfma_f32_16x16x32_bf16 v[82:85], v[190:193], v[214:217], v[82:85]
	v_mfma_f32_16x16x32_bf16 v[70:73], v[146:149], v[222:225], v[70:73]
	v_mfma_f32_16x16x32_bf16 v[66:69], v[190:193], v[222:225], v[66:69]
	v_mfma_f32_16x16x32_bf16 v[118:121], v[170:173], v[202:205], v[118:121]
	v_mfma_f32_16x16x32_bf16 v[114:117], v[194:197], v[202:205], v[114:117]
	v_mfma_f32_16x16x32_bf16 v[102:105], v[170:173], v[210:213], v[102:105]
	v_mfma_f32_16x16x32_bf16 v[98:101], v[194:197], v[210:213], v[98:101]
	v_mfma_f32_16x16x32_bf16 v[86:89], v[170:173], v[218:221], v[86:89]
	v_mfma_f32_16x16x32_bf16 v[82:85], v[194:197], v[218:221], v[82:85]
	v_mfma_f32_16x16x32_bf16 v[70:73], v[170:173], v[226:229], v[70:73]
	v_mfma_f32_16x16x32_bf16 v[66:69], v[194:197], v[226:229], v[66:69]
	s_setprio 0
	s_barrier
	s_add_i32 s94, s94, s16
	v_lshl_add_u64 v[150:151], s[12:13], 0, v[156:157]
	s_mov_b32 m0, s94
	ds_read_b128 v[198:201], v186 offset:16384
	ds_read_b128 v[202:205], v186 offset:17408
	ds_read_b128 v[206:209], v186 offset:18432
	ds_read_b128 v[210:213], v186 offset:19456
	ds_read_b128 v[214:217], v186 offset:20480
	ds_read_b128 v[218:221], v186 offset:21504
	ds_read_b128 v[222:225], v186 offset:22528
	ds_read_b128 v[226:229], v186 offset:23552
	global_load_lds_dwordx4 v[150:151], off
	s_add_i32 m0, s94, 0x2000
	s_add_u32 s94, s12, 0x40000
	v_lshl_add_u64 v[166:167], s[12:13], 0, v[160:161]
	s_addc_u32 s95, s13, 0
	s_add_i32 vcc_hi, vcc_hi, s16
	global_load_lds_dwordx4 v[166:167], off
	v_lshl_add_u64 v[230:231], s[94:95], 0, v[156:157]
	s_mov_b32 m0, vcc_hi
	v_lshl_add_u64 v[232:233], s[44:45], 0, v[158:159]
	global_load_lds_dwordx4 v[230:231], off
	v_lshl_add_u64 v[230:231], s[94:95], 0, v[160:161]
	s_add_i32 m0, vcc_hi, 0x2000
	s_nop 0
	global_load_lds_dwordx4 v[230:231], off
	v_lshl_add_u64 v[230:231], s[44:45], 0, v[154:155]
	s_mov_b32 m0, s17
	s_nop 0
	global_load_lds_dwordx4 v[230:231], off
	s_mov_b32 m0, s51
	s_nop 0
	global_load_lds_dwordx4 v[232:233], off
	s_waitcnt vmcnt(8)
	s_waitcnt lgkmcnt(0)
	s_barrier
	s_setprio 1
	s_waitcnt lgkmcnt(0)
	v_mfma_f32_16x16x32_bf16 v[62:65], v[130:133], v[198:201], v[62:65]
	v_mfma_f32_16x16x32_bf16 v[58:61], v[138:141], v[198:201], v[58:61]
	v_mfma_f32_16x16x32_bf16 v[46:49], v[130:133], v[206:209], v[46:49]
	v_mfma_f32_16x16x32_bf16 v[42:45], v[138:141], v[206:209], v[42:45]
	v_mfma_f32_16x16x32_bf16 v[30:33], v[130:133], v[214:217], v[30:33]
	v_mfma_f32_16x16x32_bf16 v[26:29], v[138:141], v[214:217], v[26:29]
	v_mfma_f32_16x16x32_bf16 v[14:17], v[130:133], v[222:225], v[14:17]
	v_mfma_f32_16x16x32_bf16 v[10:13], v[138:141], v[222:225], v[10:13]
	v_mfma_f32_16x16x32_bf16 v[62:65], v[134:137], v[202:205], v[62:65]
	v_mfma_f32_16x16x32_bf16 v[58:61], v[142:145], v[202:205], v[58:61]
	v_mfma_f32_16x16x32_bf16 v[46:49], v[134:137], v[210:213], v[46:49]
	v_mfma_f32_16x16x32_bf16 v[42:45], v[142:145], v[210:213], v[42:45]
	v_mfma_f32_16x16x32_bf16 v[30:33], v[134:137], v[218:221], v[30:33]
	v_mfma_f32_16x16x32_bf16 v[26:29], v[142:145], v[218:221], v[26:29]
	v_mfma_f32_16x16x32_bf16 v[14:17], v[134:137], v[226:229], v[14:17]
	v_mfma_f32_16x16x32_bf16 v[10:13], v[142:145], v[226:229], v[10:13]
	v_mfma_f32_16x16x32_bf16 v[54:57], v[146:149], v[198:201], v[54:57]
	v_mfma_f32_16x16x32_bf16 v[50:53], v[190:193], v[198:201], v[50:53]
	v_mfma_f32_16x16x32_bf16 v[38:41], v[146:149], v[206:209], v[38:41]
	v_mfma_f32_16x16x32_bf16 v[34:37], v[190:193], v[206:209], v[34:37]
	v_mfma_f32_16x16x32_bf16 v[22:25], v[146:149], v[214:217], v[22:25]
	v_mfma_f32_16x16x32_bf16 v[18:21], v[190:193], v[214:217], v[18:21]
	v_mfma_f32_16x16x32_bf16 v[6:9], v[146:149], v[222:225], v[6:9]
	v_mfma_f32_16x16x32_bf16 v[2:5], v[190:193], v[222:225], v[2:5]
	v_mfma_f32_16x16x32_bf16 v[54:57], v[170:173], v[202:205], v[54:57]
	v_mfma_f32_16x16x32_bf16 v[50:53], v[194:197], v[202:205], v[50:53]
	v_mfma_f32_16x16x32_bf16 v[38:41], v[170:173], v[210:213], v[38:41]
	v_mfma_f32_16x16x32_bf16 v[34:37], v[194:197], v[210:213], v[34:37]
	v_mfma_f32_16x16x32_bf16 v[22:25], v[170:173], v[218:221], v[22:25]
	v_mfma_f32_16x16x32_bf16 v[18:21], v[194:197], v[218:221], v[18:21]
	v_mfma_f32_16x16x32_bf16 v[6:9], v[170:173], v[226:229], v[6:9]
	v_mfma_f32_16x16x32_bf16 v[2:5], v[194:197], v[226:229], v[2:5]
	s_setprio 0
	s_barrier
; #define PG8_STAGE(bufoff, gbase, voff) do { _Pragma("unroll") for (int _i = 0; _i < 2; ++_i) \
;         __builtin_amdgcn_global_load_lds((const unsigned*)((const char*)(gbase) + (voff)[_i]), (PG8_LAS unsigned*)(lds + (bufoff) + ldsw + _i * 8192), 16, 0, 0); } while (0)
; #define PG8_LDA(dst, b, h) do { _Pragma("unroll") for (int m = 0; m < 4; ++m) _Pragma("unroll") for (int k = 0; k < 2; ++k) dst[m][k] = *(const PG8_LAS bf16x8*)(lds + PG8_SA(b, h) + aoff + m * 2048 + k * 1024); } while (0)
; #define PG8_LDB(dst, b, h) do { _Pragma("unroll") for (int n = 0; n < 2; ++n) _Pragma("unroll") for (int k = 0; k < 2; ++k) dst[n][k] = *(const PG8_LAS bf16x8*)(lds + PG8_SB(b, h) + boff + n * 2048 + k * 1024); } while (0)
; #define PG8_MMA(ai, bj, At, Bt) do { __builtin_amdgcn_s_setprio(1); _Pragma("unroll") for (int m = 0; m < 4; ++m) _Pragma("unroll") for (int n = 0; n < 2; ++n) _Pragma("unroll") for (int k = 0; k < 2; ++k) \
;         acc[ai][bj][m][n] = __builtin_amdgcn_mfma_f32_16x16x32_bf16(Bt[n][k], At[m][k], acc[ai][bj][m][n], 0, 0, 0); __builtin_amdgcn_s_setprio(0); } while (0)
; #define PG8_WAIT_V(n) asm volatile("s_waitcnt vmcnt(" #n ")" ::: "memory")
; #define PG8_WAIT_L(n) asm volatile("s_waitcnt lgkmcnt(" #n ")" ::: "memory")
; #define PG8_BAR __builtin_amdgcn_s_barrier()
; #define PG8_SCHED __builtin_amdgcn_sched_barrier(0)
; template <class Epi, class Sched, bool ALIGN_EPI = false, bool SP2 = false>
; __device__ __forceinline__ void gemm_phase(PG8_LAS unsigned char* lds, const Gemm g, const Sched& S, const Epi& E) {
;     ...
;             PG8_LDB(B0, 1, 0); PG8_LDB(B1, 1, 1); PG8_SCHED; PG8_LDA(At, 1, 0); PG8_STAGE(PG8_SA(0, 1), a2 + hstepA, voffA);
;             PG8_WAIT_V(8); PG8_WAIT_L(0); PG8_BAR; PG8_MMA(0, 0, At, B0); PG8_MMA(0, 1, At, B1); PG8_BAR; PG8_SCHED;
	s_add_i32 s94, 0, 0x18000
	v_add_u32_e32 v0, s94, v179
	s_add_i32 s95, 0, 0x1c000
	ds_read_b128 v[130:133], v0
	ds_read_b128 v[134:137], v0 offset:1024
	ds_read_b128 v[138:141], v0 offset:2048
	ds_read_b128 v[142:145], v0 offset:3072
	v_add_u32_e32 v0, s95, v179
	ds_read_b128 v[146:149], v0
	ds_read_b128 v[170:173], v0 offset:1024
	ds_read_b128 v[190:193], v0 offset:2048
	ds_read_b128 v[194:197], v0 offset:3072
	s_add_u32 s44, s44, 0x40000
	s_addc_u32 s45, s45, 0
	s_mov_b32 m0, s35
	v_lshl_add_u64 v[234:235], s[44:45], 0, v[154:155]
	ds_read_b128 v[198:201], v186 offset:32768
	ds_read_b128 v[202:205], v186 offset:33792
	ds_read_b128 v[206:209], v186 offset:34816
	ds_read_b128 v[210:213], v186 offset:35840
	ds_read_b128 v[214:217], v186 offset:36864
	ds_read_b128 v[218:221], v186 offset:37888
	ds_read_b128 v[222:225], v186 offset:38912
	ds_read_b128 v[226:229], v186 offset:39936
	global_load_lds_dwordx4 v[234:235], off
	v_lshl_add_u64 v[234:235], s[44:45], 0, v[158:159]
	s_mov_b32 m0, s30
	s_nop 0
	global_load_lds_dwordx4 v[234:235], off
	s_waitcnt vmcnt(8)
	s_waitcnt lgkmcnt(0)
	s_barrier
	s_setprio 1
	s_waitcnt lgkmcnt(0)
	v_mfma_f32_16x16x32_bf16 v[126:129], v[130:133], v[198:201], v[126:129]
	v_mfma_f32_16x16x32_bf16 v[122:125], v[138:141], v[198:201], v[122:125]
	v_mfma_f32_16x16x32_bf16 v[110:113], v[130:133], v[206:209], v[110:113]
	v_mfma_f32_16x16x32_bf16 v[106:109], v[138:141], v[206:209], v[106:109]
	v_mfma_f32_16x16x32_bf16 v[94:97], v[130:133], v[214:217], v[94:97]
	v_mfma_f32_16x16x32_bf16 v[90:93], v[138:141], v[214:217], v[90:93]
	v_mfma_f32_16x16x32_bf16 v[78:81], v[130:133], v[222:225], v[78:81]
	v_mfma_f32_16x16x32_bf16 v[74:77], v[138:141], v[222:225], v[74:77]
	v_mfma_f32_16x16x32_bf16 v[126:129], v[134:137], v[202:205], v[126:129]
	v_mfma_f32_16x16x32_bf16 v[122:125], v[142:145], v[202:205], v[122:125]
	v_mfma_f32_16x16x32_bf16 v[110:113], v[134:137], v[210:213], v[110:113]
	v_mfma_f32_16x16x32_bf16 v[106:109], v[142:145], v[210:213], v[106:109]
	v_mfma_f32_16x16x32_bf16 v[94:97], v[134:137], v[218:221], v[94:97]
	v_mfma_f32_16x16x32_bf16 v[90:93], v[142:145], v[218:221], v[90:93]
	v_mfma_f32_16x16x32_bf16 v[78:81], v[134:137], v[226:229], v[78:81]
	v_mfma_f32_16x16x32_bf16 v[74:77], v[142:145], v[226:229], v[74:77]
	v_mfma_f32_16x16x32_bf16 v[118:121], v[146:149], v[198:201], v[118:121]
	v_mfma_f32_16x16x32_bf16 v[114:117], v[190:193], v[198:201], v[114:117]
	v_mfma_f32_16x16x32_bf16 v[102:105], v[146:149], v[206:209], v[102:105]
	v_mfma_f32_16x16x32_bf16 v[98:101], v[190:193], v[206:209], v[98:101]
	v_mfma_f32_16x16x32_bf16 v[86:89], v[146:149], v[214:217], v[86:89]
	v_mfma_f32_16x16x32_bf16 v[82:85], v[190:193], v[214:217], v[82:85]
	v_mfma_f32_16x16x32_bf16 v[70:73], v[146:149], v[222:225], v[70:73]
	v_mfma_f32_16x16x32_bf16 v[66:69], v[190:193], v[222:225], v[66:69]
	v_mfma_f32_16x16x32_bf16 v[118:121], v[170:173], v[202:205], v[118:121]
	v_mfma_f32_16x16x32_bf16 v[114:117], v[194:197], v[202:205], v[114:117]
	v_mfma_f32_16x16x32_bf16 v[102:105], v[170:173], v[210:213], v[102:105]
	v_mfma_f32_16x16x32_bf16 v[98:101], v[194:197], v[210:213], v[98:101]
	v_mfma_f32_16x16x32_bf16 v[86:89], v[170:173], v[218:221], v[86:89]
	v_mfma_f32_16x16x32_bf16 v[82:85], v[194:197], v[218:221], v[82:85]
	v_mfma_f32_16x16x32_bf16 v[70:73], v[170:173], v[226:229], v[70:73]
	v_mfma_f32_16x16x32_bf16 v[66:69], v[194:197], v[226:229], v[66:69]
	s_setprio 0
	s_barrier
; #define PG8_STAGE(bufoff, gbase, voff) do { _Pragma("unroll") for (int _i = 0; _i < 2; ++_i) \
;         __builtin_amdgcn_global_load_lds((const unsigned*)((const char*)(gbase) + (voff)[_i]), (PG8_LAS unsigned*)(lds + (bufoff) + ldsw + _i * 8192), 16, 0, 0); } while (0)
; #define PG8_LDA(dst, b, h) do { _Pragma("unroll") for (int m = 0; m < 4; ++m) _Pragma("unroll") for (int k = 0; k < 2; ++k) dst[m][k] = *(const PG8_LAS bf16x8*)(lds + PG8_SA(b, h) + aoff + m * 2048 + k * 1024); } while (0)
; #define PG8_MMA(ai, bj, At, Bt) do { __builtin_amdgcn_s_setprio(1); _Pragma("unroll") for (int m = 0; m < 4; ++m) _Pragma("unroll") for (int n = 0; n < 2; ++n) _Pragma("unroll") for (int k = 0; k < 2; ++k) \
;         acc[ai][bj][m][n] = __builtin_amdgcn_mfma_f32_16x16x32_bf16(Bt[n][k], At[m][k], acc[ai][bj][m][n], 0, 0, 0); __builtin_amdgcn_s_setprio(0); } while (0)
; #define PG8_WAIT_V(n) asm volatile("s_waitcnt vmcnt(" #n ")" ::: "memory")
; #define PG8_WAIT_L(n) asm volatile("s_waitcnt lgkmcnt(" #n ")" ::: "memory")
; #define PG8_BAR __builtin_amdgcn_s_barrier()
; #define PG8_SCHED __builtin_amdgcn_sched_barrier(0)
; template <class Epi, class Sched, bool ALIGN_EPI = false, bool SP2 = false>
; __device__ __forceinline__ void gemm_phase(PG8_LAS unsigned char* lds, const Gemm g, const Sched& S, const Epi& E) {
;     ...
;             PG8_LDA(At, 1, 1); PG8_STAGE(PG8_SB(1, 0), b3, voffB); PG8_STAGE(PG8_SB(1, 1), b3 + hstep, voffB); PG8_STAGE(PG8_SA(1, 0), a3, voffA);
;             PG8_WAIT_V(8); PG8_WAIT_L(0); PG8_BAR; PG8_MMA(1, 0, At, B0); PG8_MMA(1, 1, At, B1); PG8_BAR; PG8_SCHED;
	s_add_i32 s44, s94, s16
	v_lshl_add_u64 v[150:151], v[150:151], 0, s[48:49]
	s_mov_b32 m0, s44
	ds_read_b128 v[198:201], v186 offset:49152
	ds_read_b128 v[202:205], v186 offset:50176
	ds_read_b128 v[206:209], v186 offset:51200
	ds_read_b128 v[210:213], v186 offset:52224
	ds_read_b128 v[214:217], v186 offset:53248
	ds_read_b128 v[218:221], v186 offset:54272
	ds_read_b128 v[222:225], v186 offset:55296
	ds_read_b128 v[226:229], v186 offset:56320
	global_load_lds_dwordx4 v[150:151], off
	s_add_i32 m0, s44, 0x2000
	s_add_u32 s12, s12, 0x40080
	v_lshl_add_u64 v[150:151], v[166:167], 0, s[48:49]
	s_addc_u32 s13, s13, 0
	s_add_i32 s44, s95, s16
	global_load_lds_dwordx4 v[150:151], off
	v_lshl_add_u64 v[150:151], s[12:13], 0, v[156:157]
	s_mov_b32 m0, s44
	s_nop 0
	global_load_lds_dwordx4 v[150:151], off
	v_lshl_add_u64 v[150:151], s[12:13], 0, v[160:161]
	s_add_i32 m0, s44, 0x2000
	s_nop 0
	global_load_lds_dwordx4 v[150:151], off
	v_lshl_add_u64 v[150:151], v[230:231], 0, s[48:49]
	s_mov_b32 m0, s59
	s_nop 0
	global_load_lds_dwordx4 v[150:151], off
	v_lshl_add_u64 v[150:151], v[232:233], 0, s[48:49]
	s_mov_b32 m0, s86
	s_nop 0
	global_load_lds_dwordx4 v[150:151], off
	s_waitcnt vmcnt(8)
	s_waitcnt lgkmcnt(0)
	s_barrier
	s_setprio 1
	s_waitcnt lgkmcnt(0)
	v_mfma_f32_16x16x32_bf16 v[62:65], v[130:133], v[198:201], v[62:65]
	v_mfma_f32_16x16x32_bf16 v[58:61], v[138:141], v[198:201], v[58:61]
	v_mfma_f32_16x16x32_bf16 v[46:49], v[130:133], v[206:209], v[46:49]
	v_mfma_f32_16x16x32_bf16 v[42:45], v[138:141], v[206:209], v[42:45]
	v_mfma_f32_16x16x32_bf16 v[30:33], v[130:133], v[214:217], v[30:33]
	v_mfma_f32_16x16x32_bf16 v[26:29], v[138:141], v[214:217], v[26:29]
	v_mfma_f32_16x16x32_bf16 v[14:17], v[130:133], v[222:225], v[14:17]
	v_mfma_f32_16x16x32_bf16 v[10:13], v[138:141], v[222:225], v[10:13]
	v_mfma_f32_16x16x32_bf16 v[62:65], v[134:137], v[202:205], v[62:65]
	v_mfma_f32_16x16x32_bf16 v[58:61], v[142:145], v[202:205], v[58:61]
	v_mfma_f32_16x16x32_bf16 v[46:49], v[134:137], v[210:213], v[46:49]
	v_mfma_f32_16x16x32_bf16 v[42:45], v[142:145], v[210:213], v[42:45]
	v_mfma_f32_16x16x32_bf16 v[30:33], v[134:137], v[218:221], v[30:33]
	v_mfma_f32_16x16x32_bf16 v[26:29], v[142:145], v[218:221], v[26:29]
	v_mfma_f32_16x16x32_bf16 v[14:17], v[134:137], v[226:229], v[14:17]
	v_mfma_f32_16x16x32_bf16 v[10:13], v[142:145], v[226:229], v[10:13]
	v_mfma_f32_16x16x32_bf16 v[54:57], v[146:149], v[198:201], v[54:57]
	v_mfma_f32_16x16x32_bf16 v[50:53], v[190:193], v[198:201], v[50:53]
	v_mfma_f32_16x16x32_bf16 v[38:41], v[146:149], v[206:209], v[38:41]
	v_mfma_f32_16x16x32_bf16 v[34:37], v[190:193], v[206:209], v[34:37]
	v_mfma_f32_16x16x32_bf16 v[22:25], v[146:149], v[214:217], v[22:25]
	v_mfma_f32_16x16x32_bf16 v[18:21], v[190:193], v[214:217], v[18:21]
	v_mfma_f32_16x16x32_bf16 v[6:9], v[146:149], v[222:225], v[6:9]
	v_mfma_f32_16x16x32_bf16 v[2:5], v[190:193], v[222:225], v[2:5]
	v_mfma_f32_16x16x32_bf16 v[54:57], v[170:173], v[202:205], v[54:57]
	v_mfma_f32_16x16x32_bf16 v[50:53], v[194:197], v[202:205], v[50:53]
	v_mfma_f32_16x16x32_bf16 v[38:41], v[170:173], v[210:213], v[38:41]
	v_mfma_f32_16x16x32_bf16 v[34:37], v[194:197], v[210:213], v[34:37]
	v_mfma_f32_16x16x32_bf16 v[22:25], v[170:173], v[218:221], v[22:25]
	v_mfma_f32_16x16x32_bf16 v[18:21], v[194:197], v[218:221], v[18:21]
	v_mfma_f32_16x16x32_bf16 v[6:9], v[170:173], v[226:229], v[6:9]
	v_mfma_f32_16x16x32_bf16 v[2:5], v[194:197], v[226:229], v[2:5]
	s_setprio 0
	s_barrier
	s_add_i32 vcc_lo, vcc_lo, 2
	s_add_u32 s10, s10, 0x100
	s_addc_u32 s11, s11, 0
	s_add_u32 s47, s47, 0x100
	s_addc_u32 s63, s63, 0
	s_cmp_gt_u32 vcc_lo, 13
	s_cbranch_scc0 .LBB0_246
	s_and_b64 vcc, exec, s[88:89]
	s_cbranch_vccz .LBB0_249
	s_barrier

; #define PG8_STAGE(bufoff, gbase, voff) do { _Pragma("unroll") for (int _i = 0; _i < 2; ++_i) \
;         __builtin_amdgcn_global_load_lds((const unsigned*)((const char*)(gbase) + (voff)[_i]), (PG8_LAS unsigned*)(lds + (bufoff) + ldsw + _i * 8192), 16, 0, 0); } while (0)
; #define PG8_LDA(dst, b, h) do { _Pragma("unroll") for (int m = 0; m < 4; ++m) _Pragma("unroll") for (int k = 0; k < 2; ++k) dst[m][k] = *(const PG8_LAS bf16x8*)(lds + PG8_SA(b, h) + aoff + m * 2048 + k * 1024); } while (0)
; #define PG8_LDB(dst, b, h) do { _Pragma("unroll") for (int n = 0; n < 2; ++n) _Pragma("unroll") for (int k = 0; k < 2; ++k) dst[n][k] = *(const PG8_LAS bf16x8*)(lds + PG8_SB(b, h) + boff + n * 2048 + k * 1024); } while (0)
; #define PG8_MMA(ai, bj, At, Bt) do { __builtin_amdgcn_s_setprio(1); _Pragma("unroll") for (int m = 0; m < 4; ++m) _Pragma("unroll") for (int n = 0; n < 2; ++n) _Pragma("unroll") for (int k = 0; k < 2; ++k) \
;         acc[ai][bj][m][n] = __builtin_amdgcn_mfma_f32_16x16x32_bf16(Bt[n][k], At[m][k], acc[ai][bj][m][n], 0, 0, 0); __builtin_amdgcn_s_setprio(0); } while (0)
; template <class Epi, class Sched, bool ALIGN_EPI = false, bool SP2 = false>
; __device__ __forceinline__ void gemm_phase(PG8_LAS unsigned char* lds, const Gemm g, const Sched& S, const Epi& E) {
;     ...
;         for (int t = 0; t < nt; t += 2) {
;             if constexpr (Epi::MIDSCALE) { if (t == (nt >> 1)) E.midscale(acc, cur, wr, fr, ui); }
;             const bool last = (t == nt - 2);
;             const char* a1 = cA + (size_t)(t >> 1) * apair + kstep;
;             const char* a2 = last ? nA : cA + (size_t)((t >> 1) + 1) * apair; const char* b2 = last ? nB : cB + (size_t)(t + 2) * kstep;
;             const char* a3 = a2 + kstep; const char* b3 = b2 + kstep;
;             if (last && has_next) S.a_ready(nxt, ui + 1);
;             if constexpr (SP2) {
;             PG8_LDB(B0, 0, 0); PG8_LDB(B1, 0, 1); PG8_SCHED; PG8_LDA(At, 0, 0); PG8_STAGE(PG8_SA(1, 1), a1 + hstepA, voffA);
;             PG8_WAIT_V(8); PG8_WAIT_L(0); PG8_BAR; PG8_MMA(0, 0, At, B0); PG8_MMA(0, 1, At, B1); PG8_BAR; PG8_SCHED;
;             PG8_LDA(At, 0, 1); PG8_STAGE(PG8_SB(0, 0), b2, voffB); PG8_STAGE(PG8_SB(0, 1), b2 + hstep, voffB); PG8_STAGE(PG8_SA(0, 0), a2, voffA);
;             PG8_WAIT_V(8); PG8_WAIT_L(0); PG8_BAR; PG8_MMA(1, 0, At, B0); PG8_MMA(1, 1, At, B1); PG8_BAR; PG8_SCHED;
.LBB0_386:
	s_add_u32 s66, s42, s64
	s_addc_u32 s67, s43, s65
	s_add_u32 s66, s66, 0x1080000
	s_addc_u32 s67, s67, 0
	s_and_b64 s[44:45], s[44:45], exec
	s_cselect_b32 s45, s51, s67
	s_cselect_b32 s44, s78, s66
	s_cselect_b32 s67, s79, s84
	s_cselect_b32 s66, s80, s83
	s_add_i32 s86, 0, 0x10000
	v_add_u32_e32 v0, s86, v154
	s_add_i32 s88, 0, 0x14000
	ds_read_b128 v[158:161], v0
	ds_read_b128 v[162:165], v0 offset:1024
	ds_read_b128 v[178:181], v0 offset:2048
	ds_read_b128 v[182:185], v0 offset:3072
	v_add_u32_e32 v0, s88, v154
	ds_read_b128 v[186:189], v0
	ds_read_b128 v[190:193], v0 offset:1024
	ds_read_b128 v[194:197], v0 offset:2048
	ds_read_b128 v[198:201], v0 offset:3072
	v_lshl_add_u64 v[2:3], v[144:145], 0, s[64:65]
	s_add_i32 m0, s35, 0xc000
	ds_read_b128 v[202:205], v156
	ds_read_b128 v[206:209], v156 offset:1024
	ds_read_b128 v[210:213], v156 offset:2048
	ds_read_b128 v[214:217], v156 offset:3072
	ds_read_b128 v[218:221], v156 offset:4096
	ds_read_b128 v[222:225], v156 offset:5120
	ds_read_b128 v[226:229], v156 offset:6144
	ds_read_b128 v[230:233], v156 offset:7168
	global_load_lds_dwordx4 v[2:3], off
	v_lshl_add_u64 v[2:3], v[146:147], 0, s[64:65]
	s_add_i32 m0, s35, 0xe000
	s_nop 0
	global_load_lds_dwordx4 v[2:3], off
	s_waitcnt vmcnt(8)
	s_waitcnt lgkmcnt(0)
	s_barrier
	s_setprio 1
	s_waitcnt lgkmcnt(0)
	v_mfma_f32_16x16x32_bf16 v[128:131], v[158:161], v[202:205], v[128:131]
	v_mfma_f32_16x16x32_bf16 v[124:127], v[178:181], v[202:205], v[124:127]
	v_mfma_f32_16x16x32_bf16 v[112:115], v[158:161], v[210:213], v[112:115]
	v_mfma_f32_16x16x32_bf16 v[108:111], v[178:181], v[210:213], v[108:111]
	v_mfma_f32_16x16x32_bf16 v[96:99], v[158:161], v[218:221], v[96:99]
	v_mfma_f32_16x16x32_bf16 v[92:95], v[178:181], v[218:221], v[92:95]
	v_mfma_f32_16x16x32_bf16 v[80:83], v[158:161], v[226:229], v[80:83]
	v_mfma_f32_16x16x32_bf16 v[76:79], v[178:181], v[226:229], v[76:79]
	v_mfma_f32_16x16x32_bf16 v[128:131], v[162:165], v[206:209], v[128:131]
	v_mfma_f32_16x16x32_bf16 v[124:127], v[182:185], v[206:209], v[124:127]
	v_mfma_f32_16x16x32_bf16 v[112:115], v[162:165], v[214:217], v[112:115]
	v_mfma_f32_16x16x32_bf16 v[108:111], v[182:185], v[214:217], v[108:111]
	v_mfma_f32_16x16x32_bf16 v[96:99], v[162:165], v[222:225], v[96:99]
	v_mfma_f32_16x16x32_bf16 v[92:95], v[182:185], v[222:225], v[92:95]
	v_mfma_f32_16x16x32_bf16 v[80:83], v[162:165], v[230:233], v[80:83]
	v_mfma_f32_16x16x32_bf16 v[76:79], v[182:185], v[230:233], v[76:79]
	v_mfma_f32_16x16x32_bf16 v[120:123], v[186:189], v[202:205], v[120:123]
	v_mfma_f32_16x16x32_bf16 v[116:119], v[194:197], v[202:205], v[116:119]
	v_mfma_f32_16x16x32_bf16 v[104:107], v[186:189], v[210:213], v[104:107]
	v_mfma_f32_16x16x32_bf16 v[100:103], v[194:197], v[210:213], v[100:103]
	v_mfma_f32_16x16x32_bf16 v[88:91], v[186:189], v[218:221], v[88:91]
	v_mfma_f32_16x16x32_bf16 v[84:87], v[194:197], v[218:221], v[84:87]
	v_mfma_f32_16x16x32_bf16 v[72:75], v[186:189], v[226:229], v[72:75]
	v_mfma_f32_16x16x32_bf16 v[68:71], v[194:197], v[226:229], v[68:71]
	v_mfma_f32_16x16x32_bf16 v[120:123], v[190:193], v[206:209], v[120:123]
	v_mfma_f32_16x16x32_bf16 v[116:119], v[198:201], v[206:209], v[116:119]
	v_mfma_f32_16x16x32_bf16 v[104:107], v[190:193], v[214:217], v[104:107]
	v_mfma_f32_16x16x32_bf16 v[100:103], v[198:201], v[214:217], v[100:103]
	v_mfma_f32_16x16x32_bf16 v[88:91], v[190:193], v[222:225], v[88:91]
	v_mfma_f32_16x16x32_bf16 v[84:87], v[198:201], v[222:225], v[84:87]
	v_mfma_f32_16x16x32_bf16 v[72:75], v[190:193], v[230:233], v[72:75]
	v_mfma_f32_16x16x32_bf16 v[68:71], v[198:201], v[230:233], v[68:71]
	s_setprio 0
	s_barrier
	s_add_i32 s86, s86, s30
	v_lshl_add_u64 v[150:151], s[66:67], 0, v[134:135]
	s_mov_b32 m0, s86
	ds_read_b128 v[202:205], v156 offset:16384
	ds_read_b128 v[206:209], v156 offset:17408
	ds_read_b128 v[210:213], v156 offset:18432
	ds_read_b128 v[214:217], v156 offset:19456
	ds_read_b128 v[218:221], v156 offset:20480
	ds_read_b128 v[222:225], v156 offset:21504
	ds_read_b128 v[226:229], v156 offset:22528
	ds_read_b128 v[230:233], v156 offset:23552
	global_load_lds_dwordx4 v[150:151], off
	s_add_i32 m0, s86, 0x2000
	s_add_u32 s86, s66, 0x80000
	v_lshl_add_u64 v[166:167], s[66:67], 0, v[138:139]
	s_addc_u32 s87, s67, 0
	s_add_i32 s88, s88, s30
	global_load_lds_dwordx4 v[166:167], off
	v_lshl_add_u64 v[2:3], s[86:87], 0, v[134:135]
	s_mov_b32 m0, s88
	v_lshl_add_u64 v[170:171], s[44:45], 0, v[132:133]
	global_load_lds_dwordx4 v[2:3], off
	v_lshl_add_u64 v[2:3], s[86:87], 0, v[138:139]
	s_add_i32 m0, s88, 0x2000
	v_lshl_add_u64 v[172:173], s[44:45], 0, v[136:137]
	global_load_lds_dwordx4 v[2:3], off
	s_mov_b32 m0, s35
	s_nop 0
	global_load_lds_dwordx4 v[170:171], off
	s_mov_b32 m0, s46
	s_nop 0
	global_load_lds_dwordx4 v[172:173], off
	s_waitcnt vmcnt(8)
	s_waitcnt lgkmcnt(0)
	s_barrier
; #define PG8_STAGE(bufoff, gbase, voff) do { _Pragma("unroll") for (int _i = 0; _i < 2; ++_i) \
;         __builtin_amdgcn_global_load_lds((const unsigned*)((const char*)(gbase) + (voff)[_i]), (PG8_LAS unsigned*)(lds + (bufoff) + ldsw + _i * 8192), 16, 0, 0); } while (0)
; #define PG8_LDA(dst, b, h) do { _Pragma("unroll") for (int m = 0; m < 4; ++m) _Pragma("unroll") for (int k = 0; k < 2; ++k) dst[m][k] = *(const PG8_LAS bf16x8*)(lds + PG8_SA(b, h) + aoff + m * 2048 + k * 1024); } while (0)
; #define PG8_LDB(dst, b, h) do { _Pragma("unroll") for (int n = 0; n < 2; ++n) _Pragma("unroll") for (int k = 0; k < 2; ++k) dst[n][k] = *(const PG8_LAS bf16x8*)(lds + PG8_SB(b, h) + boff + n * 2048 + k * 1024); } while (0)
; #define PG8_MMA(ai, bj, At, Bt) do { __builtin_amdgcn_s_setprio(1); _Pragma("unroll") for (int m = 0; m < 4; ++m) _Pragma("unroll") for (int n = 0; n < 2; ++n) _Pragma("unroll") for (int k = 0; k < 2; ++k) \
;         acc[ai][bj][m][n] = __builtin_amdgcn_mfma_f32_16x16x32_bf16(Bt[n][k], At[m][k], acc[ai][bj][m][n], 0, 0, 0); __builtin_amdgcn_s_setprio(0); } while (0)
; #define PG8_WAIT_V(n) asm volatile("s_waitcnt vmcnt(" #n ")" ::: "memory")
; #define PG8_WAIT_L(n) asm volatile("s_waitcnt lgkmcnt(" #n ")" ::: "memory")
; #define PG8_BAR __builtin_amdgcn_s_barrier()
; #define PG8_SCHED __builtin_amdgcn_sched_barrier(0)
; template <class Epi, class Sched, bool ALIGN_EPI = false, bool SP2 = false>
; __device__ __forceinline__ void gemm_phase(PG8_LAS unsigned char* lds, const Gemm g, const Sched& S, const Epi& E) {
;     ...
;             PG8_WAIT_V(8); PG8_WAIT_L(0); PG8_BAR; PG8_MMA(1, 0, At, B0); PG8_MMA(1, 1, At, B1); PG8_BAR; PG8_SCHED;
;             PG8_LDB(B0, 1, 0); PG8_LDB(B1, 1, 1); PG8_SCHED; PG8_LDA(At, 1, 0); PG8_STAGE(PG8_SA(0, 1), a2 + hstepA, voffA);
;             PG8_WAIT_V(8); PG8_WAIT_L(0); PG8_BAR; PG8_MMA(0, 0, At, B0); PG8_MMA(0, 1, At, B1); PG8_BAR; PG8_SCHED;
	s_setprio 1
	s_waitcnt lgkmcnt(0)
	v_mfma_f32_16x16x32_bf16 v[64:67], v[158:161], v[202:205], v[64:67]
	v_mfma_f32_16x16x32_bf16 v[60:63], v[178:181], v[202:205], v[60:63]
	v_mfma_f32_16x16x32_bf16 v[48:51], v[158:161], v[210:213], v[48:51]
	v_mfma_f32_16x16x32_bf16 v[44:47], v[178:181], v[210:213], v[44:47]
	v_mfma_f32_16x16x32_bf16 v[32:35], v[158:161], v[218:221], v[32:35]
	v_mfma_f32_16x16x32_bf16 v[28:31], v[178:181], v[218:221], v[28:31]
	v_mfma_f32_16x16x32_bf16 v[16:19], v[158:161], v[226:229], v[16:19]
	v_mfma_f32_16x16x32_bf16 v[12:15], v[178:181], v[226:229], v[12:15]
	v_mfma_f32_16x16x32_bf16 v[64:67], v[162:165], v[206:209], v[64:67]
	v_mfma_f32_16x16x32_bf16 v[60:63], v[182:185], v[206:209], v[60:63]
	v_mfma_f32_16x16x32_bf16 v[48:51], v[162:165], v[214:217], v[48:51]
	v_mfma_f32_16x16x32_bf16 v[44:47], v[182:185], v[214:217], v[44:47]
	v_mfma_f32_16x16x32_bf16 v[32:35], v[162:165], v[222:225], v[32:35]
	v_mfma_f32_16x16x32_bf16 v[28:31], v[182:185], v[222:225], v[28:31]
	v_mfma_f32_16x16x32_bf16 v[16:19], v[162:165], v[230:233], v[16:19]
	v_mfma_f32_16x16x32_bf16 v[12:15], v[182:185], v[230:233], v[12:15]
	v_mfma_f32_16x16x32_bf16 v[56:59], v[186:189], v[202:205], v[56:59]
	v_mfma_f32_16x16x32_bf16 v[52:55], v[194:197], v[202:205], v[52:55]
	v_mfma_f32_16x16x32_bf16 v[40:43], v[186:189], v[210:213], v[40:43]
	v_mfma_f32_16x16x32_bf16 v[36:39], v[194:197], v[210:213], v[36:39]
	v_mfma_f32_16x16x32_bf16 v[24:27], v[186:189], v[218:221], v[24:27]
	v_mfma_f32_16x16x32_bf16 v[20:23], v[194:197], v[218:221], v[20:23]
	v_mfma_f32_16x16x32_bf16 v[8:11], v[186:189], v[226:229], v[8:11]
	v_mfma_f32_16x16x32_bf16 v[2:5], v[194:197], v[226:229], v[4:7]
	v_mfma_f32_16x16x32_bf16 v[56:59], v[190:193], v[206:209], v[56:59]
	v_mfma_f32_16x16x32_bf16 v[52:55], v[198:201], v[206:209], v[52:55]
	v_mfma_f32_16x16x32_bf16 v[40:43], v[190:193], v[214:217], v[40:43]
	v_mfma_f32_16x16x32_bf16 v[36:39], v[198:201], v[214:217], v[36:39]
	v_mfma_f32_16x16x32_bf16 v[24:27], v[190:193], v[222:225], v[24:27]
	v_mfma_f32_16x16x32_bf16 v[20:23], v[198:201], v[222:225], v[20:23]
	v_mfma_f32_16x16x32_bf16 v[8:11], v[190:193], v[230:233], v[8:11]
	v_mfma_f32_16x16x32_bf16 v[2:5], v[198:201], v[230:233], v[2:5]
	s_setprio 0
	s_barrier
	s_add_i32 s86, 0, 0x18000
	v_add_u32_e32 v0, s86, v154
	s_add_i32 s87, 0, 0x1c000
	ds_read_b128 v[158:161], v0
	ds_read_b128 v[162:165], v0 offset:1024
	ds_read_b128 v[178:181], v0 offset:2048
	ds_read_b128 v[182:185], v0 offset:3072
	v_add_u32_e32 v0, s87, v154
	ds_read_b128 v[186:189], v0
	ds_read_b128 v[190:193], v0 offset:1024
	ds_read_b128 v[194:197], v0 offset:2048
	ds_read_b128 v[198:201], v0 offset:3072
	s_add_u32 s44, s44, 0x8000
	s_addc_u32 s45, s45, 0
	s_mov_b32 m0, s47
	v_lshl_add_u64 v[6:7], s[44:45], 0, v[132:133]
	ds_read_b128 v[202:205], v156 offset:32768
	ds_read_b128 v[206:209], v156 offset:33792
	ds_read_b128 v[210:213], v156 offset:34816
	ds_read_b128 v[214:217], v156 offset:35840
	ds_read_b128 v[218:221], v156 offset:36864
	ds_read_b128 v[222:225], v156 offset:37888
	ds_read_b128 v[226:229], v156 offset:38912
	ds_read_b128 v[230:233], v156 offset:39936
	global_load_lds_dwordx4 v[6:7], off
	v_lshl_add_u64 v[6:7], s[44:45], 0, v[136:137]
	s_mov_b32 m0, s68
	s_nop 0
	global_load_lds_dwordx4 v[6:7], off
	s_waitcnt vmcnt(8)
	s_waitcnt lgkmcnt(0)
	s_barrier
	s_setprio 1
	s_waitcnt lgkmcnt(0)
	v_mfma_f32_16x16x32_bf16 v[128:131], v[158:161], v[202:205], v[128:131]
	v_mfma_f32_16x16x32_bf16 v[124:127], v[178:181], v[202:205], v[124:127]
	v_mfma_f32_16x16x32_bf16 v[112:115], v[158:161], v[210:213], v[112:115]
	v_mfma_f32_16x16x32_bf16 v[108:111], v[178:181], v[210:213], v[108:111]
	v_mfma_f32_16x16x32_bf16 v[96:99], v[158:161], v[218:221], v[96:99]
	v_mfma_f32_16x16x32_bf16 v[92:95], v[178:181], v[218:221], v[92:95]
	v_mfma_f32_16x16x32_bf16 v[80:83], v[158:161], v[226:229], v[80:83]
	v_mfma_f32_16x16x32_bf16 v[76:79], v[178:181], v[226:229], v[76:79]
	v_mfma_f32_16x16x32_bf16 v[128:131], v[162:165], v[206:209], v[128:131]
	v_mfma_f32_16x16x32_bf16 v[124:127], v[182:185], v[206:209], v[124:127]
	v_mfma_f32_16x16x32_bf16 v[112:115], v[162:165], v[214:217], v[112:115]
	v_mfma_f32_16x16x32_bf16 v[108:111], v[182:185], v[214:217], v[108:111]
	v_mfma_f32_16x16x32_bf16 v[96:99], v[162:165], v[222:225], v[96:99]
	v_mfma_f32_16x16x32_bf16 v[92:95], v[182:185], v[222:225], v[92:95]
	v_mfma_f32_16x16x32_bf16 v[80:83], v[162:165], v[230:233], v[80:83]
	v_mfma_f32_16x16x32_bf16 v[76:79], v[182:185], v[230:233], v[76:79]
	v_mfma_f32_16x16x32_bf16 v[120:123], v[186:189], v[202:205], v[120:123]
	v_mfma_f32_16x16x32_bf16 v[116:119], v[194:197], v[202:205], v[116:119]
	v_mfma_f32_16x16x32_bf16 v[104:107], v[186:189], v[210:213], v[104:107]
	v_mfma_f32_16x16x32_bf16 v[100:103], v[194:197], v[210:213], v[100:103]
	v_mfma_f32_16x16x32_bf16 v[88:91], v[186:189], v[218:221], v[88:91]
	v_mfma_f32_16x16x32_bf16 v[84:87], v[194:197], v[218:221], v[84:87]
	v_mfma_f32_16x16x32_bf16 v[72:75], v[186:189], v[226:229], v[72:75]
	v_mfma_f32_16x16x32_bf16 v[68:71], v[194:197], v[226:229], v[68:71]
	v_mfma_f32_16x16x32_bf16 v[120:123], v[190:193], v[206:209], v[120:123]
	v_mfma_f32_16x16x32_bf16 v[116:119], v[198:201], v[206:209], v[116:119]
	v_mfma_f32_16x16x32_bf16 v[104:107], v[190:193], v[214:217], v[104:107]
	v_mfma_f32_16x16x32_bf16 v[100:103], v[198:201], v[214:217], v[100:103]
	v_mfma_f32_16x16x32_bf16 v[88:91], v[190:193], v[222:225], v[88:91]
	v_mfma_f32_16x16x32_bf16 v[84:87], v[198:201], v[222:225], v[84:87]
	v_mfma_f32_16x16x32_bf16 v[72:75], v[190:193], v[230:233], v[72:75]
	v_mfma_f32_16x16x32_bf16 v[68:71], v[198:201], v[230:233], v[68:71]
	s_setprio 0
	s_barrier
; #define PG8_STAGE(bufoff, gbase, voff) do { _Pragma("unroll") for (int _i = 0; _i < 2; ++_i) \
;         __builtin_amdgcn_global_load_lds((const unsigned*)((const char*)(gbase) + (voff)[_i]), (PG8_LAS unsigned*)(lds + (bufoff) + ldsw + _i * 8192), 16, 0, 0); } while (0)
; #define PG8_LDA(dst, b, h) do { _Pragma("unroll") for (int m = 0; m < 4; ++m) _Pragma("unroll") for (int k = 0; k < 2; ++k) dst[m][k] = *(const PG8_LAS bf16x8*)(lds + PG8_SA(b, h) + aoff + m * 2048 + k * 1024); } while (0)
; #define PG8_MMA(ai, bj, At, Bt) do { __builtin_amdgcn_s_setprio(1); _Pragma("unroll") for (int m = 0; m < 4; ++m) _Pragma("unroll") for (int n = 0; n < 2; ++n) _Pragma("unroll") for (int k = 0; k < 2; ++k) \
;         acc[ai][bj][m][n] = __builtin_amdgcn_mfma_f32_16x16x32_bf16(Bt[n][k], At[m][k], acc[ai][bj][m][n], 0, 0, 0); __builtin_amdgcn_s_setprio(0); } while (0)
; #define PG8_WAIT_V(n) asm volatile("s_waitcnt vmcnt(" #n ")" ::: "memory")
; #define PG8_WAIT_L(n) asm volatile("s_waitcnt lgkmcnt(" #n ")" ::: "memory")
; #define PG8_BAR __builtin_amdgcn_s_barrier()
; #define PG8_SCHED __builtin_amdgcn_sched_barrier(0)
; template <class Epi, class Sched, bool ALIGN_EPI = false, bool SP2 = false>
; __device__ __forceinline__ void gemm_phase(PG8_LAS unsigned char* lds, const Gemm g, const Sched& S, const Epi& E) {
;     ...
;             PG8_LDA(At, 1, 1); PG8_STAGE(PG8_SB(1, 0), b3, voffB); PG8_STAGE(PG8_SB(1, 1), b3 + hstep, voffB); PG8_STAGE(PG8_SA(1, 0), a3, voffA);
;             PG8_WAIT_V(8); PG8_WAIT_L(0); PG8_BAR; PG8_MMA(1, 0, At, B0); PG8_MMA(1, 1, At, B1); PG8_BAR; PG8_SCHED;
	s_add_i32 s44, s86, s30
	v_lshl_add_u64 v[6:7], v[150:151], 0, s[48:49]
	s_mov_b32 m0, s44
	ds_read_b128 v[202:205], v156 offset:49152
	ds_read_b128 v[206:209], v156 offset:50176
	ds_read_b128 v[210:213], v156 offset:51200
	ds_read_b128 v[214:217], v156 offset:52224
	ds_read_b128 v[218:221], v156 offset:53248
	ds_read_b128 v[222:225], v156 offset:54272
	ds_read_b128 v[226:229], v156 offset:55296
	ds_read_b128 v[230:233], v156 offset:56320
	global_load_lds_dwordx4 v[6:7], off
	s_add_i32 m0, s44, 0x2000
	s_add_u32 s44, s66, 0x80080
	v_lshl_add_u64 v[6:7], v[166:167], 0, s[48:49]
	s_addc_u32 s45, s67, 0
	s_add_i32 s66, s87, s30
	global_load_lds_dwordx4 v[6:7], off
	v_lshl_add_u64 v[6:7], s[44:45], 0, v[134:135]
	s_mov_b32 m0, s66
	s_nop 0
	global_load_lds_dwordx4 v[6:7], off
	v_lshl_add_u64 v[6:7], s[44:45], 0, v[138:139]
	s_add_i32 m0, s66, 0x2000
	s_nop 0
	global_load_lds_dwordx4 v[6:7], off
	v_lshl_add_u64 v[6:7], v[170:171], 0, s[48:49]
	s_mov_b32 m0, s71
	s_nop 0
	global_load_lds_dwordx4 v[6:7], off
	v_lshl_add_u64 v[6:7], v[172:173], 0, s[48:49]
	s_mov_b32 m0, s72
	s_nop 0
	global_load_lds_dwordx4 v[6:7], off
	s_waitcnt vmcnt(8)
	s_waitcnt lgkmcnt(0)
	s_barrier
	s_setprio 1
	s_waitcnt lgkmcnt(0)
	v_mfma_f32_16x16x32_bf16 v[64:67], v[158:161], v[202:205], v[64:67]
	v_mfma_f32_16x16x32_bf16 v[60:63], v[178:181], v[202:205], v[60:63]
	v_mfma_f32_16x16x32_bf16 v[48:51], v[158:161], v[210:213], v[48:51]
	v_mfma_f32_16x16x32_bf16 v[44:47], v[178:181], v[210:213], v[44:47]
	v_mfma_f32_16x16x32_bf16 v[32:35], v[158:161], v[218:221], v[32:35]
	v_mfma_f32_16x16x32_bf16 v[28:31], v[178:181], v[218:221], v[28:31]
	v_mfma_f32_16x16x32_bf16 v[16:19], v[158:161], v[226:229], v[16:19]
	v_mfma_f32_16x16x32_bf16 v[12:15], v[178:181], v[226:229], v[12:15]
	v_mfma_f32_16x16x32_bf16 v[64:67], v[162:165], v[206:209], v[64:67]
	v_mfma_f32_16x16x32_bf16 v[60:63], v[182:185], v[206:209], v[60:63]
	v_mfma_f32_16x16x32_bf16 v[48:51], v[162:165], v[214:217], v[48:51]
	v_mfma_f32_16x16x32_bf16 v[44:47], v[182:185], v[214:217], v[44:47]
	v_mfma_f32_16x16x32_bf16 v[32:35], v[162:165], v[222:225], v[32:35]
	v_mfma_f32_16x16x32_bf16 v[28:31], v[182:185], v[222:225], v[28:31]
	v_mfma_f32_16x16x32_bf16 v[16:19], v[162:165], v[230:233], v[16:19]
	v_mfma_f32_16x16x32_bf16 v[12:15], v[182:185], v[230:233], v[12:15]
	v_mfma_f32_16x16x32_bf16 v[56:59], v[186:189], v[202:205], v[56:59]
	v_mfma_f32_16x16x32_bf16 v[52:55], v[194:197], v[202:205], v[52:55]
	v_mfma_f32_16x16x32_bf16 v[40:43], v[186:189], v[210:213], v[40:43]
	v_mfma_f32_16x16x32_bf16 v[36:39], v[194:197], v[210:213], v[36:39]
	v_mfma_f32_16x16x32_bf16 v[24:27], v[186:189], v[218:221], v[24:27]
	v_mfma_f32_16x16x32_bf16 v[20:23], v[194:197], v[218:221], v[20:23]
	v_mfma_f32_16x16x32_bf16 v[6:9], v[186:189], v[226:229], v[8:11]
	v_mfma_f32_16x16x32_bf16 v[2:5], v[194:197], v[226:229], v[2:5]
	v_mfma_f32_16x16x32_bf16 v[56:59], v[190:193], v[206:209], v[56:59]
	v_mfma_f32_16x16x32_bf16 v[52:55], v[198:201], v[206:209], v[52:55]
	v_mfma_f32_16x16x32_bf16 v[40:43], v[190:193], v[214:217], v[40:43]
	v_mfma_f32_16x16x32_bf16 v[36:39], v[198:201], v[214:217], v[36:39]
	v_mfma_f32_16x16x32_bf16 v[24:27], v[190:193], v[222:225], v[24:27]
	v_mfma_f32_16x16x32_bf16 v[20:23], v[198:201], v[222:225], v[20:23]
	v_mfma_f32_16x16x32_bf16 v[8:11], v[190:193], v[230:233], v[6:9]
	v_mfma_f32_16x16x32_bf16 v[4:7], v[198:201], v[230:233], v[2:5]
	s_setprio 0
	s_barrier
	s_add_i32 s85, s85, 2
	s_add_u32 s83, s83, 0x100
	s_addc_u32 s84, s84, 0
	s_add_u32 s64, s64, 0x1080000
	s_addc_u32 s65, s65, 0
	s_cmp_gt_u32 s85, 29
	s_cbranch_scc1 .LBB0_392

; #define PG8_STAGE(bufoff, gbase, voff) do { _Pragma("unroll") for (int _i = 0; _i < 2; ++_i) \
;         __builtin_amdgcn_global_load_lds((const unsigned*)((const char*)(gbase) + (voff)[_i]), (PG8_LAS unsigned*)(lds + (bufoff) + ldsw + _i * 8192), 16, 0, 0); } while (0)
; #define PG8_LDA(dst, b, h) do { _Pragma("unroll") for (int m = 0; m < 4; ++m) _Pragma("unroll") for (int k = 0; k < 2; ++k) dst[m][k] = *(const PG8_LAS bf16x8*)(lds + PG8_SA(b, h) + aoff + m * 2048 + k * 1024); } while (0)
; #define PG8_LDB(dst, b, h) do { _Pragma("unroll") for (int n = 0; n < 2; ++n) _Pragma("unroll") for (int k = 0; k < 2; ++k) dst[n][k] = *(const PG8_LAS bf16x8*)(lds + PG8_SB(b, h) + boff + n * 2048 + k * 1024); } while (0)
; #define PG8_MMA(ai, bj, At, Bt) do { __builtin_amdgcn_s_setprio(1); _Pragma("unroll") for (int m = 0; m < 4; ++m) _Pragma("unroll") for (int n = 0; n < 2; ++n) _Pragma("unroll") for (int k = 0; k < 2; ++k) \
;         acc[ai][bj][m][n] = __builtin_amdgcn_mfma_f32_16x16x32_bf16(Bt[n][k], At[m][k], acc[ai][bj][m][n], 0, 0, 0); __builtin_amdgcn_s_setprio(0); } while (0)
; #define PG8_WAIT_V(n) asm volatile("s_waitcnt vmcnt(" #n ")" ::: "memory")
; #define PG8_WAIT_L(n) asm volatile("s_waitcnt lgkmcnt(" #n ")" ::: "memory")
; #define PG8_BAR __builtin_amdgcn_s_barrier()
; #define PG8_SCHED __builtin_amdgcn_sched_barrier(0)
; template <class Epi, class Sched, bool ALIGN_EPI = false, bool SP2 = false>
; __device__ __forceinline__ void gemm_phase(PG8_LAS unsigned char* lds, const Gemm g, const Sched& S, const Epi& E) {
;     ...
;         PG8_WAIT_V(2); PG8_BAR;
;         PG8_STAGE(PG8_SB(1, 0), cB + kstep, voffB); PG8_STAGE(PG8_SA(1, 0), cA + kstep, voffA); PG8_STAGE(PG8_SB(1, 1), cB + hstep + kstep, voffB);
;         PG8_WAIT_V(6); PG8_BAR;
;     ...
;             PG8_LDB(B0, 0, 0); PG8_LDB(B1, 0, 1); PG8_SCHED; PG8_LDA(At, 0, 0); PG8_STAGE(PG8_SA(1, 1), a1 + hstepA, voffA);
;             PG8_WAIT_V(8); PG8_WAIT_L(0); PG8_BAR; PG8_MMA(0, 0, At, B0); PG8_MMA(0, 1, At, B1); PG8_BAR; PG8_SCHED;
.LBB0_417:
	s_add_i32 s42, 0, 0x18000
	s_and_b32 s0, s0, 3
	s_add_i32 s30, s42, s12
	s_lshl_b32 s7, s0, 12
	s_lshl_b32 s13, s6, 13
	v_lshl_add_u64 v[18:19], v[2:3], 0, s[48:49]
	s_mov_b32 m0, s30
	s_add_i32 s46, s30, 0x2000
	s_add_i32 s35, s16, 0x8000
	s_add_i32 s47, s16, 0xa000
	s_waitcnt vmcnt(2)
	s_barrier
	global_load_lds_dwordx4 v[18:19], off
	v_lshl_add_u64 v[22:23], v[4:5], 0, s[48:49]
	s_mov_b32 m0, s46
	s_add_u32 s26, s4, 0x80080
	global_load_lds_dwordx4 v[22:23], off
	v_lshl_add_u64 v[16:17], v[20:21], 0, s[48:49]
	s_mov_b32 m0, s35
	s_addc_u32 s27, s5, 0
	s_add_i32 s43, 0, 0x1c000
	global_load_lds_dwordx4 v[16:17], off
	v_lshl_add_u64 v[24:25], v[28:29], 0, s[48:49]
	s_mov_b32 m0, s47
	s_add_i32 s50, s43, s12
	global_load_lds_dwordx4 v[24:25], off
	v_lshl_add_u64 v[30:31], s[26:27], 0, v[0:1]
	s_mov_b32 m0, s50
	s_add_i32 s51, s50, 0x2000
	global_load_lds_dwordx4 v[30:31], off
	v_lshl_add_u64 v[32:33], s[26:27], 0, v[34:35]
	s_mov_b32 m0, s51
	v_and_b32_e32 v6, 15, v36
	global_load_lds_dwordx4 v[32:33], off
	v_and_b32_e32 v134, 48, v36
	v_lshlrev_b32_e32 v7, 2, v36
	v_lshl_or_b32 v132, s6, 6, v6
	v_lshl_or_b32 v6, v6, 6, v134
	v_and_b32_e32 v7, 32, v7
	v_bitop3_b32 v36, v6, s7, v7 bitop3:0xde
	s_add_i32 s58, 0, 0x10000
	s_add_i32 s60, 0, 0x14000
	v_add_u32_e32 v135, s42, v36
	s_add_u32 s42, s20, 0x1080000
	v_add_u32_e32 v177, s43, v36
	s_addc_u32 s43, s21, 0
	s_add_u32 s6, s20, 0x1080080
	s_addc_u32 s7, s21, 0
	v_add_u32_e32 v128, s58, v36
	s_add_u32 s64, s20, 0x8080
	s_waitcnt vmcnt(6)
	s_barrier
	v_add_u32_e32 v129, s60, v36
	s_addc_u32 s65, s21, 0
	s_add_i32 s58, s58, s12
	ds_read_b128 v[36:39], v128
	ds_read_b128 v[40:43], v128 offset:1024
	ds_read_b128 v[44:47], v128 offset:2048
	ds_read_b128 v[48:51], v128 offset:3072
	ds_read_b128 v[52:55], v129
	ds_read_b128 v[56:59], v129 offset:1024
	ds_read_b128 v[60:63], v129 offset:2048
	ds_read_b128 v[64:67], v129 offset:3072
	s_add_i32 s63, s16, 0xc000
	s_add_i32 s62, s16, 0xe000
	s_add_i32 s53, s58, 0x2000
	s_add_u32 s44, s4, 0x80100
	s_addc_u32 s45, s5, 0
	s_add_i32 s60, s60, s12
	s_add_i32 s59, s60, 0x2000
	s_add_u32 s26, s20, 0x1088000
	s_addc_u32 s27, s21, 0
	s_add_u32 s12, s4, 0x80180
	v_bitop3_b32 v6, v6, s13, v7 bitop3:0xde
	s_addc_u32 s13, s5, 0
	s_add_u32 s4, s20, 0x1088080
	s_addc_u32 s5, s21, 0
	v_add_u32_e32 v133, 0, v6
	s_cmpk_gt_u32 s61, 0xff
	s_mov_b32 m0, s63
	v_lshl_add_u64 v[6:7], s[64:65], 0, v[8:9]
	ds_read_b128 v[68:71], v133
	ds_read_b128 v[72:75], v133 offset:1024
	ds_read_b128 v[76:79], v133 offset:2048
	ds_read_b128 v[80:83], v133 offset:3072
	ds_read_b128 v[84:87], v133 offset:4096
	ds_read_b128 v[88:91], v133 offset:5120
	ds_read_b128 v[92:95], v133 offset:6144
	ds_read_b128 v[96:99], v133 offset:7168
	global_load_lds_dwordx4 v[6:7], off
	v_lshl_add_u64 v[6:7], s[64:65], 0, v[26:27]
	s_mov_b32 m0, s62
	s_nop 0
	global_load_lds_dwordx4 v[6:7], off
	s_waitcnt vmcnt(8)
	s_waitcnt lgkmcnt(0)
	s_barrier
	s_setprio 1
	s_waitcnt lgkmcnt(0)
	v_mfma_f32_16x16x32_bf16 v[100:103], v[36:39], v[68:71], 0
	v_mfma_f32_16x16x32_bf16 v[104:107], v[44:47], v[68:71], 0
	v_mfma_f32_16x16x32_bf16 v[108:111], v[36:39], v[76:79], 0
	v_mfma_f32_16x16x32_bf16 v[112:115], v[44:47], v[76:79], 0
	v_mfma_f32_16x16x32_bf16 v[116:119], v[36:39], v[84:87], 0
	v_mfma_f32_16x16x32_bf16 v[120:123], v[44:47], v[84:87], 0
	v_mfma_f32_16x16x32_bf16 v[124:127], v[36:39], v[92:95], 0
	v_mfma_f32_16x16x32_bf16 v[136:139], v[44:47], v[92:95], 0
	v_mfma_f32_16x16x32_bf16 v[100:103], v[40:43], v[72:75], v[100:103]
	v_mfma_f32_16x16x32_bf16 v[104:107], v[48:51], v[72:75], v[104:107]
	v_mfma_f32_16x16x32_bf16 v[108:111], v[40:43], v[80:83], v[108:111]
	v_mfma_f32_16x16x32_bf16 v[112:115], v[48:51], v[80:83], v[112:115]
	v_mfma_f32_16x16x32_bf16 v[116:119], v[40:43], v[88:91], v[116:119]
	v_mfma_f32_16x16x32_bf16 v[120:123], v[48:51], v[88:91], v[120:123]
	v_mfma_f32_16x16x32_bf16 v[124:127], v[40:43], v[96:99], v[124:127]
	v_mfma_f32_16x16x32_bf16 v[136:139], v[48:51], v[96:99], v[136:139]
	v_mfma_f32_16x16x32_bf16 v[140:143], v[52:55], v[68:71], 0
	v_mfma_f32_16x16x32_bf16 v[68:71], v[60:63], v[68:71], 0
	v_mfma_f32_16x16x32_bf16 v[140:143], v[56:59], v[72:75], v[140:143]
	v_mfma_f32_16x16x32_bf16 v[68:71], v[64:67], v[72:75], v[68:71]
	v_mfma_f32_16x16x32_bf16 v[72:75], v[52:55], v[76:79], 0
	v_mfma_f32_16x16x32_bf16 v[76:79], v[60:63], v[76:79], 0
	v_mfma_f32_16x16x32_bf16 v[72:75], v[56:59], v[80:83], v[72:75]
	v_mfma_f32_16x16x32_bf16 v[76:79], v[64:67], v[80:83], v[76:79]
	v_mfma_f32_16x16x32_bf16 v[80:83], v[52:55], v[84:87], 0
	v_mfma_f32_16x16x32_bf16 v[84:87], v[60:63], v[84:87], 0
	v_mfma_f32_16x16x32_bf16 v[80:83], v[56:59], v[88:91], v[80:83]
	v_mfma_f32_16x16x32_bf16 v[84:87], v[64:67], v[88:91], v[84:87]
	v_mfma_f32_16x16x32_bf16 v[88:91], v[52:55], v[92:95], 0
	v_mfma_f32_16x16x32_bf16 v[92:95], v[60:63], v[92:95], 0
	v_mfma_f32_16x16x32_bf16 v[88:91], v[56:59], v[96:99], v[88:91]
	v_mfma_f32_16x16x32_bf16 v[92:95], v[64:67], v[96:99], v[92:95]
	s_setprio 0
	s_barrier
	s_mov_b64 s[20:21], 0x100
	s_mov_b32 m0, s58
	v_lshl_add_u64 v[6:7], v[2:3], 0, s[20:21]
	ds_read_b128 v[96:99], v133 offset:16384
	ds_read_b128 v[144:147], v133 offset:17408
	ds_read_b128 v[154:157], v133 offset:18432
	ds_read_b128 v[158:161], v133 offset:19456
	ds_read_b128 v[162:165], v133 offset:20480
	ds_read_b128 v[178:181], v133 offset:21504
	ds_read_b128 v[182:185], v133 offset:22528
	ds_read_b128 v[186:189], v133 offset:23552
	global_load_lds_dwordx4 v[6:7], off
	v_lshl_add_u64 v[6:7], v[4:5], 0, s[20:21]
	s_mov_b32 m0, s53
	s_nop 0
	global_load_lds_dwordx4 v[6:7], off
	v_lshl_add_u64 v[6:7], s[44:45], 0, v[0:1]
	s_mov_b32 m0, s60
	s_nop 0
	global_load_lds_dwordx4 v[6:7], off
	v_lshl_add_u64 v[6:7], s[44:45], 0, v[34:35]
	s_mov_b32 m0, s59
	s_nop 0
	global_load_lds_dwordx4 v[6:7], off
	v_lshl_add_u64 v[6:7], s[42:43], 0, v[8:9]
	s_mov_b32 m0, s16
	s_nop 0
	global_load_lds_dwordx4 v[6:7], off
	v_lshl_add_u64 v[6:7], s[42:43], 0, v[26:27]
	s_mov_b32 m0, s52
	s_nop 0
	global_load_lds_dwordx4 v[6:7], off
	s_waitcnt vmcnt(8)
	s_waitcnt lgkmcnt(0)
	s_barrier
; #define PG8_STAGE(bufoff, gbase, voff) do { _Pragma("unroll") for (int _i = 0; _i < 2; ++_i) \
;         __builtin_amdgcn_global_load_lds((const unsigned*)((const char*)(gbase) + (voff)[_i]), (PG8_LAS unsigned*)(lds + (bufoff) + ldsw + _i * 8192), 16, 0, 0); } while (0)
; #define PG8_LDA(dst, b, h) do { _Pragma("unroll") for (int m = 0; m < 4; ++m) _Pragma("unroll") for (int k = 0; k < 2; ++k) dst[m][k] = *(const PG8_LAS bf16x8*)(lds + PG8_SA(b, h) + aoff + m * 2048 + k * 1024); } while (0)
; #define PG8_LDB(dst, b, h) do { _Pragma("unroll") for (int n = 0; n < 2; ++n) _Pragma("unroll") for (int k = 0; k < 2; ++k) dst[n][k] = *(const PG8_LAS bf16x8*)(lds + PG8_SB(b, h) + boff + n * 2048 + k * 1024); } while (0)
; #define PG8_MMA(ai, bj, At, Bt) do { __builtin_amdgcn_s_setprio(1); _Pragma("unroll") for (int m = 0; m < 4; ++m) _Pragma("unroll") for (int n = 0; n < 2; ++n) _Pragma("unroll") for (int k = 0; k < 2; ++k) \
;         acc[ai][bj][m][n] = __builtin_amdgcn_mfma_f32_16x16x32_bf16(Bt[n][k], At[m][k], acc[ai][bj][m][n], 0, 0, 0); __builtin_amdgcn_s_setprio(0); } while (0)
; #define PG8_WAIT_V(n) asm volatile("s_waitcnt vmcnt(" #n ")" ::: "memory")
; #define PG8_WAIT_L(n) asm volatile("s_waitcnt lgkmcnt(" #n ")" ::: "memory")
; #define PG8_BAR __builtin_amdgcn_s_barrier()
; #define PG8_SCHED __builtin_amdgcn_sched_barrier(0)
; template <class Epi, class Sched, bool ALIGN_EPI = false, bool SP2 = false>
; __device__ __forceinline__ void gemm_phase(PG8_LAS unsigned char* lds, const Gemm g, const Sched& S, const Epi& E) {
;     ...
;             PG8_LDA(At, 0, 1); PG8_STAGE(PG8_SB(0, 0), b2, voffB); PG8_STAGE(PG8_SB(0, 1), b2 + hstep, voffB); PG8_STAGE(PG8_SA(0, 0), a2, voffA);
;             PG8_WAIT_V(8); PG8_WAIT_L(0); PG8_BAR; PG8_MMA(1, 0, At, B0); PG8_MMA(1, 1, At, B1); PG8_BAR; PG8_SCHED;
;             PG8_LDB(B0, 1, 0); PG8_LDB(B1, 1, 1); PG8_SCHED; PG8_LDA(At, 1, 0); PG8_STAGE(PG8_SA(0, 1), a2 + hstepA, voffA);
;             PG8_WAIT_V(8); PG8_WAIT_L(0); PG8_BAR; PG8_MMA(0, 0, At, B0); PG8_MMA(0, 1, At, B1); PG8_BAR; PG8_SCHED;
	s_setprio 1
	s_waitcnt lgkmcnt(0)
	v_mfma_f32_16x16x32_bf16 v[190:193], v[36:39], v[96:99], 0
	v_mfma_f32_16x16x32_bf16 v[198:201], v[36:39], v[154:157], 0
	v_mfma_f32_16x16x32_bf16 v[206:209], v[36:39], v[162:165], 0
	v_mfma_f32_16x16x32_bf16 v[36:39], v[36:39], v[182:185], 0
	v_mfma_f32_16x16x32_bf16 v[190:193], v[40:43], v[144:147], v[190:193]
	v_mfma_f32_16x16x32_bf16 v[198:201], v[40:43], v[158:161], v[198:201]
	v_mfma_f32_16x16x32_bf16 v[206:209], v[40:43], v[178:181], v[206:209]
	v_mfma_f32_16x16x32_bf16 v[36:39], v[40:43], v[186:189], v[36:39]
	v_mfma_f32_16x16x32_bf16 v[40:43], v[44:47], v[182:185], 0
	v_mfma_f32_16x16x32_bf16 v[194:197], v[44:47], v[96:99], 0
	v_mfma_f32_16x16x32_bf16 v[202:205], v[44:47], v[154:157], 0
	v_mfma_f32_16x16x32_bf16 v[210:213], v[44:47], v[162:165], 0
	v_mfma_f32_16x16x32_bf16 v[40:43], v[48:51], v[186:189], v[40:43]
	v_mfma_f32_16x16x32_bf16 v[194:197], v[48:51], v[144:147], v[194:197]
	v_mfma_f32_16x16x32_bf16 v[202:205], v[48:51], v[158:161], v[202:205]
	v_mfma_f32_16x16x32_bf16 v[210:213], v[48:51], v[178:181], v[210:213]
	v_mfma_f32_16x16x32_bf16 v[44:47], v[52:55], v[96:99], 0
	v_mfma_f32_16x16x32_bf16 v[48:51], v[60:63], v[96:99], 0
	v_mfma_f32_16x16x32_bf16 v[44:47], v[56:59], v[144:147], v[44:47]
	v_mfma_f32_16x16x32_bf16 v[48:51], v[64:67], v[144:147], v[48:51]
	v_mfma_f32_16x16x32_bf16 v[96:99], v[52:55], v[154:157], 0
	v_mfma_f32_16x16x32_bf16 v[144:147], v[60:63], v[154:157], 0
	v_mfma_f32_16x16x32_bf16 v[154:157], v[52:55], v[162:165], 0
	v_mfma_f32_16x16x32_bf16 v[52:55], v[52:55], v[182:185], 0
	v_mfma_f32_16x16x32_bf16 v[96:99], v[56:59], v[158:161], v[96:99]
	v_mfma_f32_16x16x32_bf16 v[154:157], v[56:59], v[178:181], v[154:157]
	v_mfma_f32_16x16x32_bf16 v[52:55], v[56:59], v[186:189], v[52:55]
	v_mfma_f32_16x16x32_bf16 v[56:59], v[60:63], v[182:185], 0
	v_mfma_f32_16x16x32_bf16 v[144:147], v[64:67], v[158:161], v[144:147]
	v_mfma_f32_16x16x32_bf16 v[158:161], v[60:63], v[162:165], 0
	v_mfma_f32_16x16x32_bf16 v[56:59], v[64:67], v[186:189], v[56:59]
	v_mfma_f32_16x16x32_bf16 v[158:161], v[64:67], v[178:181], v[158:161]
	s_setprio 0
	s_barrier
	ds_read_b128 v[60:63], v135
	ds_read_b128 v[64:67], v135 offset:1024
	ds_read_b128 v[162:165], v135 offset:2048
	ds_read_b128 v[178:181], v135 offset:3072
	ds_read_b128 v[182:185], v177
	ds_read_b128 v[186:189], v177 offset:1024
	ds_read_b128 v[214:217], v177 offset:2048
	ds_read_b128 v[218:221], v177 offset:3072
	s_mov_b32 m0, s17
	v_lshl_add_u64 v[6:7], s[26:27], 0, v[8:9]
	ds_read_b128 v[222:225], v133 offset:32768
	ds_read_b128 v[226:229], v133 offset:33792
	ds_read_b128 v[230:233], v133 offset:34816
	ds_read_b128 v[234:237], v133 offset:35840
	ds_read_b128 v[238:241], v133 offset:36864
	ds_read_b128 v[242:245], v133 offset:37888
	ds_read_b128 v[246:249], v133 offset:38912
	ds_read_b128 v[250:253], v133 offset:39936
	global_load_lds_dwordx4 v[6:7], off
	v_lshl_add_u64 v[6:7], s[26:27], 0, v[26:27]
	s_mov_b32 m0, s28
	s_nop 0
	global_load_lds_dwordx4 v[6:7], off
	s_waitcnt vmcnt(8)
	s_waitcnt lgkmcnt(0)
	s_barrier
	s_setprio 1
	s_waitcnt lgkmcnt(0)
	v_mfma_f32_16x16x32_bf16 v[100:103], v[60:63], v[222:225], v[100:103]
	v_mfma_f32_16x16x32_bf16 v[104:107], v[162:165], v[222:225], v[104:107]
	v_mfma_f32_16x16x32_bf16 v[108:111], v[60:63], v[230:233], v[108:111]
	v_mfma_f32_16x16x32_bf16 v[112:115], v[162:165], v[230:233], v[112:115]
	v_mfma_f32_16x16x32_bf16 v[116:119], v[60:63], v[238:241], v[116:119]
	v_mfma_f32_16x16x32_bf16 v[120:123], v[162:165], v[238:241], v[120:123]
	v_mfma_f32_16x16x32_bf16 v[124:127], v[60:63], v[246:249], v[124:127]
	v_mfma_f32_16x16x32_bf16 v[136:139], v[162:165], v[246:249], v[136:139]
	v_mfma_f32_16x16x32_bf16 v[100:103], v[64:67], v[226:229], v[100:103]
	v_mfma_f32_16x16x32_bf16 v[104:107], v[178:181], v[226:229], v[104:107]
	v_mfma_f32_16x16x32_bf16 v[108:111], v[64:67], v[234:237], v[108:111]
	v_mfma_f32_16x16x32_bf16 v[112:115], v[178:181], v[234:237], v[112:115]
	v_mfma_f32_16x16x32_bf16 v[116:119], v[64:67], v[242:245], v[116:119]
	v_mfma_f32_16x16x32_bf16 v[120:123], v[178:181], v[242:245], v[120:123]
	v_mfma_f32_16x16x32_bf16 v[124:127], v[64:67], v[250:253], v[124:127]
	v_mfma_f32_16x16x32_bf16 v[136:139], v[178:181], v[250:253], v[136:139]
	v_mfma_f32_16x16x32_bf16 v[68:71], v[214:217], v[222:225], v[68:71]
	v_mfma_f32_16x16x32_bf16 v[80:83], v[182:185], v[238:241], v[80:83]
	v_mfma_f32_16x16x32_bf16 v[84:87], v[214:217], v[238:241], v[84:87]
	v_mfma_f32_16x16x32_bf16 v[88:91], v[182:185], v[246:249], v[88:91]
	v_mfma_f32_16x16x32_bf16 v[92:95], v[214:217], v[246:249], v[92:95]
	v_mfma_f32_16x16x32_bf16 v[140:143], v[182:185], v[222:225], v[140:143]
	v_mfma_f32_16x16x32_bf16 v[68:71], v[218:221], v[226:229], v[68:71]
	v_mfma_f32_16x16x32_bf16 v[72:75], v[182:185], v[230:233], v[72:75]
	v_mfma_f32_16x16x32_bf16 v[76:79], v[214:217], v[230:233], v[76:79]
	v_mfma_f32_16x16x32_bf16 v[80:83], v[186:189], v[242:245], v[80:83]
	v_mfma_f32_16x16x32_bf16 v[84:87], v[218:221], v[242:245], v[84:87]
	v_mfma_f32_16x16x32_bf16 v[88:91], v[186:189], v[250:253], v[88:91]
	v_mfma_f32_16x16x32_bf16 v[92:95], v[218:221], v[250:253], v[92:95]
	v_mfma_f32_16x16x32_bf16 v[140:143], v[186:189], v[226:229], v[140:143]
	v_mfma_f32_16x16x32_bf16 v[72:75], v[186:189], v[234:237], v[72:75]
	v_mfma_f32_16x16x32_bf16 v[76:79], v[218:221], v[234:237], v[76:79]
	s_setprio 0
	s_barrier
; #define PG8_STAGE(bufoff, gbase, voff) do { _Pragma("unroll") for (int _i = 0; _i < 2; ++_i) \
;         __builtin_amdgcn_global_load_lds((const unsigned*)((const char*)(gbase) + (voff)[_i]), (PG8_LAS unsigned*)(lds + (bufoff) + ldsw + _i * 8192), 16, 0, 0); } while (0)
; #define PG8_LDA(dst, b, h) do { _Pragma("unroll") for (int m = 0; m < 4; ++m) _Pragma("unroll") for (int k = 0; k < 2; ++k) dst[m][k] = *(const PG8_LAS bf16x8*)(lds + PG8_SA(b, h) + aoff + m * 2048 + k * 1024); } while (0)
; #define PG8_LDB(dst, b, h) do { _Pragma("unroll") for (int n = 0; n < 2; ++n) _Pragma("unroll") for (int k = 0; k < 2; ++k) dst[n][k] = *(const PG8_LAS bf16x8*)(lds + PG8_SB(b, h) + boff + n * 2048 + k * 1024); } while (0)
; #define PG8_MMA(ai, bj, At, Bt) do { __builtin_amdgcn_s_setprio(1); _Pragma("unroll") for (int m = 0; m < 4; ++m) _Pragma("unroll") for (int n = 0; n < 2; ++n) _Pragma("unroll") for (int k = 0; k < 2; ++k) \
;         acc[ai][bj][m][n] = __builtin_amdgcn_mfma_f32_16x16x32_bf16(Bt[n][k], At[m][k], acc[ai][bj][m][n], 0, 0, 0); __builtin_amdgcn_s_setprio(0); } while (0)
; #define PG8_WAIT_V(n) asm volatile("s_waitcnt vmcnt(" #n ")" ::: "memory")
; #define PG8_WAIT_L(n) asm volatile("s_waitcnt lgkmcnt(" #n ")" ::: "memory")
; #define PG8_BAR __builtin_amdgcn_s_barrier()
; #define PG8_SCHED __builtin_amdgcn_sched_barrier(0)
; template <class Epi, class Sched, bool ALIGN_EPI = false, bool SP2 = false>
; __device__ __forceinline__ void gemm_phase(PG8_LAS unsigned char* lds, const Gemm g, const Sched& S, const Epi& E) {
;     ...
;             PG8_LDB(B0, 0, 0); PG8_LDB(B1, 0, 1); PG8_SCHED; PG8_LDA(At, 0, 0); PG8_STAGE(PG8_SA(1, 1), a1 + hstepA, voffA);
;             PG8_WAIT_V(8); PG8_WAIT_L(0); PG8_BAR; PG8_MMA(0, 0, At, B0); PG8_MMA(0, 1, At, B1); PG8_BAR; PG8_SCHED;
;     ...
;             PG8_LDA(At, 1, 1); PG8_STAGE(PG8_SB(1, 0), b3, voffB); PG8_STAGE(PG8_SB(1, 1), b3 + hstep, voffB); PG8_STAGE(PG8_SA(1, 0), a3, voffA);
;             PG8_WAIT_V(8); PG8_WAIT_L(0); PG8_BAR; PG8_MMA(1, 0, At, B0); PG8_MMA(1, 1, At, B1); PG8_BAR; PG8_SCHED;
	s_mov_b64 s[20:21], 0x180
	s_mov_b32 m0, s30
	v_lshl_add_u64 v[6:7], v[2:3], 0, s[20:21]
	ds_read_b128 v[222:225], v133 offset:49152
	ds_read_b128 v[226:229], v133 offset:50176
	ds_read_b128 v[230:233], v133 offset:51200
	ds_read_b128 v[234:237], v133 offset:52224
	ds_read_b128 v[238:241], v133 offset:53248
	ds_read_b128 v[242:245], v133 offset:54272
	ds_read_b128 v[246:249], v133 offset:55296
	ds_read_b128 v[250:253], v133 offset:56320
	global_load_lds_dwordx4 v[6:7], off
	v_lshl_add_u64 v[6:7], v[4:5], 0, s[20:21]
	s_mov_b32 m0, s46
	s_nop 0
	global_load_lds_dwordx4 v[6:7], off
	v_lshl_add_u64 v[6:7], s[12:13], 0, v[0:1]
	s_mov_b32 m0, s50
	s_nop 0
	global_load_lds_dwordx4 v[6:7], off
	v_lshl_add_u64 v[6:7], s[12:13], 0, v[34:35]
	s_mov_b32 m0, s51
	s_nop 0
	global_load_lds_dwordx4 v[6:7], off
	v_lshl_add_u64 v[6:7], s[6:7], 0, v[8:9]
	s_mov_b32 m0, s35
	s_nop 0
	global_load_lds_dwordx4 v[6:7], off
	v_lshl_add_u64 v[6:7], s[6:7], 0, v[26:27]
	s_mov_b32 m0, s47
	s_nop 0
	global_load_lds_dwordx4 v[6:7], off
	s_waitcnt vmcnt(8)
	s_waitcnt lgkmcnt(0)
	s_barrier
	s_setprio 1
	s_waitcnt lgkmcnt(0)
	v_mfma_f32_16x16x32_bf16 v[34:37], v[60:63], v[246:249], v[36:39]
	v_mfma_f32_16x16x32_bf16 v[38:41], v[162:165], v[246:249], v[40:43]
	v_mfma_f32_16x16x32_bf16 v[190:193], v[60:63], v[222:225], v[190:193]
	v_mfma_f32_16x16x32_bf16 v[194:197], v[162:165], v[222:225], v[194:197]
	v_mfma_f32_16x16x32_bf16 v[198:201], v[60:63], v[230:233], v[198:201]
	v_mfma_f32_16x16x32_bf16 v[202:205], v[162:165], v[230:233], v[202:205]
	v_mfma_f32_16x16x32_bf16 v[206:209], v[60:63], v[238:241], v[206:209]
	v_mfma_f32_16x16x32_bf16 v[210:213], v[162:165], v[238:241], v[210:213]
	v_mfma_f32_16x16x32_bf16 v[34:37], v[64:67], v[250:253], v[34:37]
	v_mfma_f32_16x16x32_bf16 v[38:41], v[178:181], v[250:253], v[38:41]
	v_mfma_f32_16x16x32_bf16 v[190:193], v[64:67], v[226:229], v[190:193]
	v_mfma_f32_16x16x32_bf16 v[194:197], v[178:181], v[226:229], v[194:197]
	v_mfma_f32_16x16x32_bf16 v[198:201], v[64:67], v[234:237], v[198:201]
	v_mfma_f32_16x16x32_bf16 v[202:205], v[178:181], v[234:237], v[202:205]
	v_mfma_f32_16x16x32_bf16 v[206:209], v[64:67], v[242:245], v[206:209]
	v_mfma_f32_16x16x32_bf16 v[210:213], v[178:181], v[242:245], v[210:213]
	v_mfma_f32_16x16x32_bf16 v[42:45], v[182:185], v[222:225], v[44:47]
	v_mfma_f32_16x16x32_bf16 v[46:49], v[214:217], v[222:225], v[48:51]
	v_mfma_f32_16x16x32_bf16 v[60:63], v[182:185], v[230:233], v[96:99]
	v_mfma_f32_16x16x32_bf16 v[64:67], v[214:217], v[230:233], v[144:147]
	v_mfma_f32_16x16x32_bf16 v[96:99], v[182:185], v[238:241], v[154:157]
	v_mfma_f32_16x16x32_bf16 v[50:53], v[182:185], v[246:249], v[52:55]
	v_mfma_f32_16x16x32_bf16 v[54:57], v[214:217], v[246:249], v[56:59]
	v_mfma_f32_16x16x32_bf16 v[42:45], v[186:189], v[226:229], v[42:45]
	v_mfma_f32_16x16x32_bf16 v[46:49], v[218:221], v[226:229], v[46:49]
	v_mfma_f32_16x16x32_bf16 v[60:63], v[186:189], v[234:237], v[60:63]
	v_mfma_f32_16x16x32_bf16 v[64:67], v[218:221], v[234:237], v[64:67]
	v_mfma_f32_16x16x32_bf16 v[96:99], v[186:189], v[242:245], v[96:99]
	v_mfma_f32_16x16x32_bf16 v[144:147], v[214:217], v[238:241], v[158:161]
	v_mfma_f32_16x16x32_bf16 v[50:53], v[186:189], v[250:253], v[50:53]
	v_mfma_f32_16x16x32_bf16 v[54:57], v[218:221], v[250:253], v[54:57]
	v_mfma_f32_16x16x32_bf16 v[144:147], v[218:221], v[242:245], v[144:147]
	s_setprio 0
	s_barrier
	ds_read_b128 v[154:157], v128
	ds_read_b128 v[158:161], v128 offset:1024
	ds_read_b128 v[162:165], v128 offset:2048
	ds_read_b128 v[178:181], v128 offset:3072
	ds_read_b128 v[182:185], v129
	ds_read_b128 v[186:189], v129 offset:1024
	ds_read_b128 v[214:217], v129 offset:2048
	ds_read_b128 v[218:221], v129 offset:3072
	s_mov_b32 m0, s63
	v_lshl_add_u64 v[6:7], s[4:5], 0, v[8:9]
	ds_read_b128 v[222:225], v133
	ds_read_b128 v[226:229], v133 offset:1024
	ds_read_b128 v[230:233], v133 offset:2048
	ds_read_b128 v[234:237], v133 offset:3072
	ds_read_b128 v[238:241], v133 offset:4096
	ds_read_b128 v[242:245], v133 offset:5120
	ds_read_b128 v[246:249], v133 offset:6144
	ds_read_b128 v[250:253], v133 offset:7168
	global_load_lds_dwordx4 v[6:7], off
	v_lshl_add_u64 v[6:7], s[4:5], 0, v[26:27]
	s_mov_b32 m0, s62
	s_nop 0
	global_load_lds_dwordx4 v[6:7], off
	s_waitcnt vmcnt(8)
	s_waitcnt lgkmcnt(0)
	s_barrier
	s_setprio 1
	s_waitcnt lgkmcnt(0)
	v_mfma_f32_16x16x32_bf16 v[112:115], v[162:165], v[230:233], v[112:115]
	v_mfma_f32_16x16x32_bf16 v[170:173], v[178:181], v[234:237], v[112:115]
	v_mfma_f32_16x16x32_bf16 v[112:115], v[154:157], v[238:241], v[116:119]
	v_mfma_f32_16x16x32_bf16 v[148:151], v[158:161], v[242:245], v[112:115]
	v_mfma_f32_16x16x32_bf16 v[112:115], v[162:165], v[238:241], v[120:123]
	v_mfma_f32_16x16x32_bf16 v[128:131], v[178:181], v[242:245], v[112:115]
	v_mfma_f32_16x16x32_bf16 v[112:115], v[154:157], v[246:249], v[124:127]
	v_mfma_f32_16x16x32_bf16 v[100:103], v[154:157], v[222:225], v[100:103]
	v_mfma_f32_16x16x32_bf16 v[104:107], v[162:165], v[222:225], v[104:107]
	v_mfma_f32_16x16x32_bf16 v[108:111], v[154:157], v[230:233], v[108:111]
	v_mfma_f32_16x16x32_bf16 v[122:125], v[158:161], v[250:253], v[112:115]
	v_mfma_f32_16x16x32_bf16 v[112:115], v[162:165], v[246:249], v[136:139]
	v_mfma_f32_16x16x32_bf16 v[100:103], v[158:161], v[226:229], v[100:103]
	v_mfma_f32_16x16x32_bf16 v[104:107], v[178:181], v[226:229], v[104:107]
	v_mfma_f32_16x16x32_bf16 v[108:111], v[158:161], v[234:237], v[108:111]
	v_mfma_f32_16x16x32_bf16 v[136:139], v[178:181], v[250:253], v[112:115]
	v_mfma_f32_16x16x32_bf16 v[72:75], v[182:185], v[230:233], v[72:75]
	v_mfma_f32_16x16x32_bf16 v[112:115], v[182:185], v[222:225], v[140:143]
	v_mfma_f32_16x16x32_bf16 v[68:71], v[214:217], v[222:225], v[68:71]
	v_mfma_f32_16x16x32_bf16 v[222:225], v[186:189], v[234:237], v[72:75]
	v_mfma_f32_16x16x32_bf16 v[72:75], v[214:217], v[230:233], v[76:79]
	v_mfma_f32_16x16x32_bf16 v[140:143], v[186:189], v[226:229], v[112:115]
	v_mfma_f32_16x16x32_bf16 v[68:71], v[218:221], v[226:229], v[68:71]
	v_mfma_f32_16x16x32_bf16 v[226:229], v[218:221], v[234:237], v[72:75]
	v_mfma_f32_16x16x32_bf16 v[72:75], v[182:185], v[238:241], v[80:83]
	v_mfma_f32_16x16x32_bf16 v[230:233], v[186:189], v[242:245], v[72:75]
	v_mfma_f32_16x16x32_bf16 v[72:75], v[214:217], v[238:241], v[84:87]
	v_mfma_f32_16x16x32_bf16 v[234:237], v[218:221], v[242:245], v[72:75]
	v_mfma_f32_16x16x32_bf16 v[72:75], v[182:185], v[246:249], v[88:91]
	v_mfma_f32_16x16x32_bf16 v[238:241], v[186:189], v[250:253], v[72:75]
	v_mfma_f32_16x16x32_bf16 v[72:75], v[214:217], v[246:249], v[92:95]
	v_mfma_f32_16x16x32_bf16 v[242:245], v[218:221], v[250:253], v[72:75]
	s_setprio 0
	s_barrier
; #define PG8_STAGE(bufoff, gbase, voff) do { _Pragma("unroll") for (int _i = 0; _i < 2; ++_i) \
;         __builtin_amdgcn_global_load_lds((const unsigned*)((const char*)(gbase) + (voff)[_i]), (PG8_LAS unsigned*)(lds + (bufoff) + ldsw + _i * 8192), 16, 0, 0); } while (0)
; #define PG8_LDA(dst, b, h) do { _Pragma("unroll") for (int m = 0; m < 4; ++m) _Pragma("unroll") for (int k = 0; k < 2; ++k) dst[m][k] = *(const PG8_LAS bf16x8*)(lds + PG8_SA(b, h) + aoff + m * 2048 + k * 1024); } while (0)
; #define PG8_LDB(dst, b, h) do { _Pragma("unroll") for (int n = 0; n < 2; ++n) _Pragma("unroll") for (int k = 0; k < 2; ++k) dst[n][k] = *(const PG8_LAS bf16x8*)(lds + PG8_SB(b, h) + boff + n * 2048 + k * 1024); } while (0)
; #define PG8_MMA(ai, bj, At, Bt) do { __builtin_amdgcn_s_setprio(1); _Pragma("unroll") for (int m = 0; m < 4; ++m) _Pragma("unroll") for (int n = 0; n < 2; ++n) _Pragma("unroll") for (int k = 0; k < 2; ++k) \
;         acc[ai][bj][m][n] = __builtin_amdgcn_mfma_f32_16x16x32_bf16(Bt[n][k], At[m][k], acc[ai][bj][m][n], 0, 0, 0); __builtin_amdgcn_s_setprio(0); } while (0)
; #define PG8_WAIT_V(n) asm volatile("s_waitcnt vmcnt(" #n ")" ::: "memory")
; #define PG8_WAIT_L(n) asm volatile("s_waitcnt lgkmcnt(" #n ")" ::: "memory")
; #define PG8_BAR __builtin_amdgcn_s_barrier()
; #define PG8_SCHED __builtin_amdgcn_sched_barrier(0)
; template <class Epi, class Sched, bool ALIGN_EPI = false, bool SP2 = false>
; __device__ __forceinline__ void gemm_phase(PG8_LAS unsigned char* lds, const Gemm g, const Sched& S, const Epi& E) {
;     ...
;             PG8_LDA(At, 0, 1); PG8_STAGE(PG8_SB(0, 0), b2, voffB); PG8_STAGE(PG8_SB(0, 1), b2 + hstep, voffB); PG8_STAGE(PG8_SA(0, 0), a2, voffA);
;             PG8_WAIT_V(8); PG8_WAIT_L(0); PG8_BAR; PG8_MMA(1, 0, At, B0); PG8_MMA(1, 1, At, B1); PG8_BAR; PG8_SCHED;
;             PG8_LDB(B0, 1, 0); PG8_LDB(B1, 1, 1); PG8_SCHED; PG8_LDA(At, 1, 0); PG8_STAGE(PG8_SA(0, 1), a2 + hstepA, voffA);
;             PG8_WAIT_V(8); PG8_WAIT_L(0); PG8_BAR; PG8_MMA(0, 0, At, B0); PG8_MMA(0, 1, At, B1); PG8_BAR; PG8_SCHED;
	s_mov_b32 m0, s58
	s_nop 3
	ds_read_b128 v[72:75], v133 offset:16384
	ds_read_b128 v[76:79], v133 offset:17408
	ds_read_b128 v[80:83], v133 offset:18432
	ds_read_b128 v[84:87], v133 offset:19456
	ds_read_b128 v[88:91], v133 offset:20480
	ds_read_b128 v[92:95], v133 offset:21504
	ds_read_b128 v[112:115], v133 offset:22528
	ds_read_b128 v[116:119], v133 offset:23552
	global_load_lds_dwordx4 v[2:3], off
	s_mov_b32 m0, s53
	s_nop 0
	global_load_lds_dwordx4 v[4:5], off
	s_mov_b32 m0, s60
	s_nop 0
	global_load_lds_dwordx4 v[12:13], off
	s_mov_b32 m0, s59
	s_nop 0
	global_load_lds_dwordx4 v[14:15], off
	s_mov_b32 m0, s16
	s_nop 0
	global_load_lds_dwordx4 v[20:21], off
	s_mov_b32 m0, s52
	s_nop 0
	global_load_lds_dwordx4 v[28:29], off
	s_waitcnt vmcnt(8)
	s_waitcnt lgkmcnt(0)
	s_barrier
	s_setprio 1
	s_waitcnt lgkmcnt(0)
	v_mfma_f32_16x16x32_bf16 v[2:5], v[154:157], v[72:75], v[190:193]
	v_mfma_f32_16x16x32_bf16 v[12:15], v[162:165], v[72:75], v[194:197]
	v_mfma_f32_16x16x32_bf16 v[26:29], v[154:157], v[80:83], v[198:201]
	v_mfma_f32_16x16x32_bf16 v[34:37], v[154:157], v[112:115], v[34:37]
	v_mfma_f32_16x16x32_bf16 v[38:41], v[162:165], v[112:115], v[38:41]
	v_mfma_f32_16x16x32_bf16 v[2:5], v[158:161], v[76:79], v[2:5]
	v_mfma_f32_16x16x32_bf16 v[12:15], v[178:181], v[76:79], v[12:15]
	v_mfma_f32_16x16x32_bf16 v[26:29], v[158:161], v[84:87], v[26:29]
	v_mfma_f32_16x16x32_bf16 v[190:193], v[162:165], v[80:83], v[202:205]
	v_mfma_f32_16x16x32_bf16 v[194:197], v[154:157], v[88:91], v[206:209]
	v_mfma_f32_16x16x32_bf16 v[198:201], v[162:165], v[88:91], v[210:213]
	v_mfma_f32_16x16x32_bf16 v[34:37], v[158:161], v[116:119], v[34:37]
	v_mfma_f32_16x16x32_bf16 v[38:41], v[178:181], v[116:119], v[38:41]
	v_mfma_f32_16x16x32_bf16 v[190:193], v[178:181], v[84:87], v[190:193]
	v_mfma_f32_16x16x32_bf16 v[194:197], v[158:161], v[92:95], v[194:197]
	v_mfma_f32_16x16x32_bf16 v[198:201], v[178:181], v[92:95], v[198:201]
	v_mfma_f32_16x16x32_bf16 v[42:45], v[182:185], v[72:75], v[42:45]
	v_mfma_f32_16x16x32_bf16 v[154:157], v[186:189], v[76:79], v[42:45]
	v_mfma_f32_16x16x32_bf16 v[42:45], v[214:217], v[72:75], v[46:49]
	v_mfma_f32_16x16x32_bf16 v[158:161], v[218:221], v[76:79], v[42:45]
	v_mfma_f32_16x16x32_bf16 v[42:45], v[182:185], v[80:83], v[60:63]
	v_mfma_f32_16x16x32_bf16 v[162:165], v[186:189], v[84:87], v[42:45]
	v_mfma_f32_16x16x32_bf16 v[42:45], v[214:217], v[80:83], v[64:67]
	v_mfma_f32_16x16x32_bf16 v[178:181], v[218:221], v[84:87], v[42:45]
	v_mfma_f32_16x16x32_bf16 v[42:45], v[182:185], v[88:91], v[96:99]
	v_mfma_f32_16x16x32_bf16 v[202:205], v[186:189], v[92:95], v[42:45]
	v_mfma_f32_16x16x32_bf16 v[42:45], v[214:217], v[88:91], v[144:147]
	v_mfma_f32_16x16x32_bf16 v[144:147], v[218:221], v[92:95], v[42:45]
	v_mfma_f32_16x16x32_bf16 v[42:45], v[182:185], v[112:115], v[50:53]
	v_mfma_f32_16x16x32_bf16 v[182:185], v[186:189], v[116:119], v[42:45]
	v_mfma_f32_16x16x32_bf16 v[42:45], v[214:217], v[112:115], v[54:57]
	v_mfma_f32_16x16x32_bf16 v[186:189], v[218:221], v[116:119], v[42:45]
	s_setprio 0
	s_barrier
	ds_read_b128 v[50:53], v135
	ds_read_b128 v[54:57], v135 offset:1024
	ds_read_b128 v[206:209], v135 offset:2048
	ds_read_b128 v[210:213], v135 offset:3072
	ds_read_b128 v[214:217], v177
	ds_read_b128 v[218:221], v177 offset:1024
	ds_read_b128 v[246:249], v177 offset:2048
	ds_read_b128 v[250:253], v177 offset:3072
	s_mov_b32 m0, s17
	ds_read_b128 v[42:45], v133 offset:32768
	ds_read_b128 v[46:49], v133 offset:33792
	ds_read_b128 v[58:61], v133 offset:34816
	ds_read_b128 v[62:65], v133 offset:35840
	ds_read_b128 v[94:97], v133 offset:36864
	ds_read_b128 v[6:9], v133 offset:37888
	ds_read_b128 v[72:75], v133 offset:38912
	ds_read_b128 v[76:79], v133 offset:39936
	global_load_lds_dwordx4 v[166:167], off
	s_mov_b32 m0, s28
	s_nop 0
	global_load_lds_dwordx4 v[10:11], off
	s_waitcnt vmcnt(8)
	s_waitcnt lgkmcnt(0)
	s_barrier
; #define PG8_STAGE(bufoff, gbase, voff) do { _Pragma("unroll") for (int _i = 0; _i < 2; ++_i) \
;         __builtin_amdgcn_global_load_lds((const unsigned*)((const char*)(gbase) + (voff)[_i]), (PG8_LAS unsigned*)(lds + (bufoff) + ldsw + _i * 8192), 16, 0, 0); } while (0)
; #define PG8_LDA(dst, b, h) do { _Pragma("unroll") for (int m = 0; m < 4; ++m) _Pragma("unroll") for (int k = 0; k < 2; ++k) dst[m][k] = *(const PG8_LAS bf16x8*)(lds + PG8_SA(b, h) + aoff + m * 2048 + k * 1024); } while (0)
; #define PG8_MMA(ai, bj, At, Bt) do { __builtin_amdgcn_s_setprio(1); _Pragma("unroll") for (int m = 0; m < 4; ++m) _Pragma("unroll") for (int n = 0; n < 2; ++n) _Pragma("unroll") for (int k = 0; k < 2; ++k) \
;         acc[ai][bj][m][n] = __builtin_amdgcn_mfma_f32_16x16x32_bf16(Bt[n][k], At[m][k], acc[ai][bj][m][n], 0, 0, 0); __builtin_amdgcn_s_setprio(0); } while (0)
; #define PG8_WAIT_V(n) asm volatile("s_waitcnt vmcnt(" #n ")" ::: "memory")
; #define PG8_WAIT_L(n) asm volatile("s_waitcnt lgkmcnt(" #n ")" ::: "memory")
; #define PG8_BAR __builtin_amdgcn_s_barrier()
; #define PG8_SCHED __builtin_amdgcn_sched_barrier(0)
; template <class Epi, class Sched, bool ALIGN_EPI = false, bool SP2 = false>
; __device__ __forceinline__ void gemm_phase(PG8_LAS unsigned char* lds, const Gemm g, const Sched& S, const Epi& E) {
;     ...
;             PG8_WAIT_V(8); PG8_WAIT_L(0); PG8_BAR; PG8_MMA(0, 0, At, B0); PG8_MMA(0, 1, At, B1); PG8_BAR; PG8_SCHED;
;             PG8_LDA(At, 1, 1); PG8_STAGE(PG8_SB(1, 0), b3, voffB); PG8_STAGE(PG8_SB(1, 1), b3 + hstep, voffB); PG8_STAGE(PG8_SA(1, 0), a3, voffA);
;             PG8_WAIT_V(8); PG8_WAIT_L(0); PG8_BAR; PG8_MMA(1, 0, At, B0); PG8_MMA(1, 1, At, B1); PG8_BAR; PG8_SCHED;
	s_setprio 1
	s_waitcnt lgkmcnt(0)
	v_mfma_f32_16x16x32_bf16 v[80:83], v[50:53], v[42:45], v[100:103]
	v_mfma_f32_16x16x32_bf16 v[114:117], v[54:57], v[46:49], v[80:83]
	v_mfma_f32_16x16x32_bf16 v[80:83], v[206:209], v[42:45], v[104:107]
	v_mfma_f32_16x16x32_bf16 v[118:121], v[210:213], v[46:49], v[80:83]
	v_mfma_f32_16x16x32_bf16 v[80:83], v[50:53], v[58:61], v[108:111]
	v_mfma_f32_16x16x32_bf16 v[98:101], v[54:57], v[62:65], v[80:83]
	v_mfma_f32_16x16x32_bf16 v[80:83], v[206:209], v[58:61], v[170:173]
	v_mfma_f32_16x16x32_bf16 v[90:93], v[50:53], v[72:75], v[122:125]
	v_mfma_f32_16x16x32_bf16 v[102:105], v[210:213], v[62:65], v[80:83]
	v_mfma_f32_16x16x32_bf16 v[80:83], v[50:53], v[94:97], v[148:151]
	v_mfma_f32_16x16x32_bf16 v[86:89], v[206:209], v[94:97], v[128:131]
	v_mfma_f32_16x16x32_bf16 v[170:173], v[54:57], v[76:79], v[90:93]
	v_mfma_f32_16x16x32_bf16 v[90:93], v[206:209], v[72:75], v[136:139]
	v_mfma_f32_16x16x32_bf16 v[82:85], v[54:57], v[6:9], v[80:83]
	v_mfma_f32_16x16x32_bf16 v[86:89], v[210:213], v[6:9], v[86:89]
	v_mfma_f32_16x16x32_bf16 v[148:151], v[210:213], v[76:79], v[90:93]
	v_mfma_f32_16x16x32_bf16 v[90:93], v[214:217], v[42:45], v[140:143]
	v_mfma_f32_16x16x32_bf16 v[42:45], v[246:249], v[42:45], v[68:71]
	v_mfma_f32_16x16x32_bf16 v[126:129], v[250:253], v[46:49], v[42:45]
	v_mfma_f32_16x16x32_bf16 v[42:45], v[214:217], v[58:61], v[222:225]
	v_mfma_f32_16x16x32_bf16 v[106:109], v[218:221], v[62:65], v[42:45]
	v_mfma_f32_16x16x32_bf16 v[42:45], v[246:249], v[58:61], v[226:229]
	v_mfma_f32_16x16x32_bf16 v[110:113], v[250:253], v[62:65], v[42:45]
	v_mfma_f32_16x16x32_bf16 v[42:45], v[214:217], v[94:97], v[230:233]
	v_mfma_f32_16x16x32_bf16 v[122:125], v[218:221], v[46:49], v[90:93]
	v_mfma_f32_16x16x32_bf16 v[90:93], v[218:221], v[6:9], v[42:45]
	v_mfma_f32_16x16x32_bf16 v[42:45], v[246:249], v[94:97], v[234:237]
	v_mfma_f32_16x16x32_bf16 v[94:97], v[250:253], v[6:9], v[42:45]
	v_mfma_f32_16x16x32_bf16 v[6:9], v[214:217], v[72:75], v[238:241]
	v_mfma_f32_16x16x32_bf16 v[136:139], v[218:221], v[76:79], v[6:9]
	v_mfma_f32_16x16x32_bf16 v[6:9], v[246:249], v[72:75], v[242:245]
	v_mfma_f32_16x16x32_bf16 v[66:69], v[250:253], v[76:79], v[6:9]
	s_setprio 0
	s_barrier
	s_mov_b32 m0, s30
	s_nop 3
	ds_read_b128 v[6:9], v133 offset:49152
	ds_read_b128 v[70:73], v133 offset:50176
	ds_read_b128 v[74:77], v133 offset:51200
	ds_read_b128 v[78:81], v133 offset:52224
	ds_read_b128 v[140:143], v133 offset:53248
	ds_read_b128 v[222:225], v133 offset:54272
	ds_read_b128 v[226:229], v133 offset:55296
	ds_read_b128 v[230:233], v133 offset:56320
	global_load_lds_dwordx4 v[18:19], off
	s_mov_b32 m0, s46
	s_nop 0
	global_load_lds_dwordx4 v[22:23], off
	s_mov_b32 m0, s50
	s_nop 0
	global_load_lds_dwordx4 v[30:31], off
	s_mov_b32 m0, s51
	s_nop 0
	global_load_lds_dwordx4 v[32:33], off
	s_mov_b32 m0, s35
	s_nop 0
	global_load_lds_dwordx4 v[16:17], off
	s_mov_b32 m0, s47
	s_nop 0
	global_load_lds_dwordx4 v[24:25], off
	s_waitcnt vmcnt(8)
	s_waitcnt lgkmcnt(0)
	s_barrier
	s_setprio 1
	s_waitcnt lgkmcnt(0)
	v_mfma_f32_16x16x32_bf16 v[2:5], v[50:53], v[6:9], v[2:5]
	v_mfma_f32_16x16x32_bf16 v[62:65], v[54:57], v[70:73], v[2:5]
	v_mfma_f32_16x16x32_bf16 v[2:5], v[206:209], v[6:9], v[12:15]
	v_mfma_f32_16x16x32_bf16 v[58:61], v[210:213], v[70:73], v[2:5]
	v_mfma_f32_16x16x32_bf16 v[2:5], v[50:53], v[74:77], v[26:29]
	v_mfma_f32_16x16x32_bf16 v[46:49], v[54:57], v[78:81], v[2:5]
	v_mfma_f32_16x16x32_bf16 v[2:5], v[206:209], v[74:77], v[190:193]
	v_mfma_f32_16x16x32_bf16 v[42:45], v[210:213], v[78:81], v[2:5]
	v_mfma_f32_16x16x32_bf16 v[2:5], v[50:53], v[140:143], v[194:197]
	v_mfma_f32_16x16x32_bf16 v[30:33], v[54:57], v[222:225], v[2:5]
	v_mfma_f32_16x16x32_bf16 v[2:5], v[206:209], v[140:143], v[198:201]
	v_mfma_f32_16x16x32_bf16 v[26:29], v[210:213], v[222:225], v[2:5]
	v_mfma_f32_16x16x32_bf16 v[2:5], v[50:53], v[226:229], v[34:37]
	v_mfma_f32_16x16x32_bf16 v[14:17], v[54:57], v[230:233], v[2:5]
	v_mfma_f32_16x16x32_bf16 v[2:5], v[206:209], v[226:229], v[38:41]
	v_mfma_f32_16x16x32_bf16 v[10:13], v[210:213], v[230:233], v[2:5]
	v_mfma_f32_16x16x32_bf16 v[2:5], v[214:217], v[6:9], v[154:157]
	v_mfma_f32_16x16x32_bf16 v[54:57], v[218:221], v[70:73], v[2:5]
	v_mfma_f32_16x16x32_bf16 v[2:5], v[246:249], v[6:9], v[158:161]
	v_mfma_f32_16x16x32_bf16 v[50:53], v[250:253], v[70:73], v[2:5]
	v_mfma_f32_16x16x32_bf16 v[2:5], v[214:217], v[74:77], v[162:165]
	v_mfma_f32_16x16x32_bf16 v[38:41], v[218:221], v[78:81], v[2:5]
	v_mfma_f32_16x16x32_bf16 v[2:5], v[246:249], v[74:77], v[178:181]
	v_mfma_f32_16x16x32_bf16 v[34:37], v[250:253], v[78:81], v[2:5]
	v_mfma_f32_16x16x32_bf16 v[2:5], v[214:217], v[140:143], v[202:205]
	v_mfma_f32_16x16x32_bf16 v[22:25], v[218:221], v[222:225], v[2:5]
	v_mfma_f32_16x16x32_bf16 v[2:5], v[246:249], v[140:143], v[144:147]
	v_mfma_f32_16x16x32_bf16 v[18:21], v[250:253], v[222:225], v[2:5]
	v_mfma_f32_16x16x32_bf16 v[2:5], v[214:217], v[226:229], v[182:185]
	v_mfma_f32_16x16x32_bf16 v[6:9], v[218:221], v[230:233], v[2:5]
	v_mfma_f32_16x16x32_bf16 v[2:5], v[246:249], v[226:229], v[186:189]
	v_mfma_f32_16x16x32_bf16 v[2:5], v[250:253], v[230:233], v[2:5]
	s_setprio 0
	s_barrier
	s_cbranch_scc1 .LBB0_419
	s_barrier
